# conv weights staged to LDS by 4 LDS-DMA per unit in the P7 ConvGLU epilogue, read with ds_read instead of 32 global loads; on top of setprio reorder
# speedup vs baseline: 1.0105x; 1.0059x over previous
; #define PG8_LAS __attribute__((address_space(3)))
; #define PG8_GAS __attribute__((address_space(1)))
;     __device__ __forceinline__ void run(f32x4 (&acc)[2][2][4][2], const Unit& un, int wr, int wc, int fr, int fq, PG8_LAS unsigned char* xl) const {
;         asm volatile("" : "+v"(fr), "+v"(fq));
;         const int cl = wc * 32 + 8 * fq;
; #pragma unroll
;         for (int ai = 0; ai < 2; ++ai)
; #pragma unroll
;             for (int m = 0; m < 4; ++m) { const float iv = __builtin_amdgcn_rsqf(ssq[(size_t)un.pm * BM + wr * 64 + fr + ai * HALF + m * 16] * inv_n + eps);
; #pragma unroll
;                 for (int bj = 0; bj < 2; ++bj)
; #pragma unroll
;                     for (int n = 0; n < 2; ++n) acc[ai][bj][m][n] = acc[ai][bj][m][n] * iv; }
;         PG8_LAS float* X = (PG8_LAS float*)xl;
; #pragma unroll
;         for (int ai = 0; ai < 2; ++ai) { const int blk = ai * 2 + wr;
;             if (fr == 0) {
; #pragma unroll
;                 for (int bj = 0; bj < 2; ++bj) { *(PG8_LAS f32x4*)(X + (blk * 2 + 0) * 256 + bj * 128 + cl) = acc[ai][bj][0][0]; *(PG8_LAS f32x4*)(X + (blk * 2 + 0) * 256 + bj * 128 + cl + 4) = acc[ai][bj][0][1]; } }
;             if (fr == 15) {
; #pragma unroll
;                 for (int bj = 0; bj < 2; ++bj) { *(PG8_LAS f32x4*)(X + (blk * 2 + 1) * 256 + bj * 128 + cl) = acc[ai][bj][3][0]; *(PG8_LAS f32x4*)(X + (blk * 2 + 1) * 256 + bj * 128 + cl + 4) = acc[ai][bj][3][1]; } } }
;     ...
;                 const f32x4 w0g = *(const PG8_GAS f32x4*)(cw + j), w1g = *(const PG8_GAS f32x4*)(cw + nup + j), w2g = *(const PG8_GAS f32x4*)(cw + 2 * (size_t)nup + j), bg = *(const PG8_GAS f32x4*)(cb + j);
;                 const f32x4 w0v = *(const PG8_GAS f32x4*)(cw + dff + j), w1v = *(const PG8_GAS f32x4*)(cw + nup + dff + j), w2v = *(const PG8_GAS f32x4*)(cw + 2 * (size_t)nup + dff + j), bv = *(const PG8_GAS f32x4*)(cb + dff + j);
.LBB0_773:
	s_lshr_b32 s98, s7, 10
	s_cmp_gt_u32 s98, 3
	s_cbranch_scc1 .Lldsw_skip
	s_mov_b32 s99, 0
	s_mov_b32 s100, 0x15800
	s_cmp_eq_u32 s98, 1
	s_cselect_b32 s99, 0x2b000, s99
	s_cselect_b32 s100, 0xac00, s100
	s_cmp_eq_u32 s98, 2
	s_cselect_b32 s99, 0x20400, s99
	s_cselect_b32 s100, 0x35c00, s100
	s_cmp_eq_u32 s98, 3
	s_cselect_b32 s99, 0, s99
	s_cselect_b32 s100, 0xac00, s100
	v_lshl_add_u32 v248, v239, 4, v238
	v_cmp_lt_u32_e32 vcc, 31, v248
	v_mov_b32_e32 v249, s99
	v_mov_b32_e32 v250, s100
	v_cndmask_b32_e32 v249, v249, v250, vcc
	v_and_b32_e32 v248, 31, v248
	v_lshlrev_b32_e32 v248, 4, v248
	s_lshl_b32 s99, s10, 9
	v_add3_u32 v248, v248, v249, s99
	s_cmp_eq_u32 s98, 3
	s_cselect_b32 vcc_lo, s22, s20
	s_cselect_b32 vcc_hi, s23, s21
	s_lshl_b32 s100, s98, 10
	s_add_i32 m0, s100, 0x22400
	s_nop 0
	global_load_lds_dwordx4 v248, vcc
.Lldsw_skip:
	s_ashr_i32 s77, s76, 31
	s_lshl_b64 s[12:13], s[76:77], 10
	v_mov_b32_e32 v210, v238
	v_mov_b32_e32 v131, v239
	s_add_u32 s12, s35, s12
	s_addc_u32 s13, s96, s13
	v_ashrrev_i32_e32 v211, 31, v210
	v_lshl_add_u64 v[132:133], v[210:211], 2, s[12:13]
	flat_load_dword v134, v[132:133] offset:192
	flat_load_dword v130, v[132:133]
	flat_load_dword v214, v[132:133] offset:64
	flat_load_dword v149, v[132:133] offset:512
	flat_load_dword v245, v[132:133] offset:576
	flat_load_dword v211, v[132:133] offset:640
	flat_load_dword v147, v[132:133] offset:704
	flat_load_dword v216, v[132:133] offset:128
	v_lshl_add_u32 v196, v131, 3, s70
	v_mov_b32_e32 v247, 0x22400
	v_lshl_add_u32 v247, v196, 2, v247
	v_cmp_lt_i32_e32 vcc, 14, v210
	s_mov_b64 s[12:13], 0
	s_waitcnt vmcnt(0) lgkmcnt(0)
	v_fmamk_f32 v132, v134, 0x39800000, v244
	v_rsq_f32_e32 v134, v132
	s_nop 0
	v_pk_mul_f32 v[120:121], v[120:121], v[134:135] op_sel_hi:[1,0]
	v_pk_mul_f32 v[118:119], v[118:119], v[134:135] op_sel_hi:[1,0]
	s_and_saveexec_b64 s[14:15], vcc
	s_xor_b64 s[14:15], exec, s[14:15]
	s_cbranch_execz .LBB0_777
	v_cmp_eq_u32_e32 vcc, 15, v210
	s_and_saveexec_b64 s[16:17], vcc
	v_lshl_add_u32 v131, v196, 2, s82
	s_mov_b64 s[12:13], exec
	v_add_u32_e32 v146, 0x400, v131
	ds_write_b128 v131, v[118:121] offset:1024
	s_or_b64 exec, exec, s[16:17]
	s_and_b64 s[12:13], s[12:13], exec

; #define PG8_LAS __attribute__((address_space(3)))
; #define PG8_GAS __attribute__((address_space(1)))
;     __device__ __forceinline__ void run(f32x4 (&acc)[2][2][4][2], const Unit& un, int wr, int wc, int fr, int fq, PG8_LAS unsigned char* xl) const {
;     ...
;         for (int ai = 0; ai < 2; ++ai) { const int blk = ai * 2 + wr;
;             u32x2 keep[4];
; #pragma unroll
;             for (int n = 0; n < 2; ++n) {
;                 const int j = un.pn * 128 + cl + 4 * n;
;                 const f32x4 w0g = *(const PG8_GAS f32x4*)(cw + j), w1g = *(const PG8_GAS f32x4*)(cw + nup + j), w2g = *(const PG8_GAS f32x4*)(cw + 2 * (size_t)nup + j), bg = *(const PG8_GAS f32x4*)(cb + j);
;                 const f32x4 w0v = *(const PG8_GAS f32x4*)(cw + dff + j), w1v = *(const PG8_GAS f32x4*)(cw + nup + dff + j), w2v = *(const PG8_GAS f32x4*)(cw + 2 * (size_t)nup + dff + j), bv = *(const PG8_GAS f32x4*)(cb + dff + j);
;                 f32x4 hpg, hpv, hng, hnv;
;                 if (blk > 0) { hpg = *(const PG8_LAS f32x4*)(X + ((blk - 1) * 2 + 1) * 256 + cl + 4 * n); hpv = *(const PG8_LAS f32x4*)(X + ((blk - 1) * 2 + 1) * 256 + 128 + cl + 4 * n); } else { hpg = (f32x4){0.f, 0.f, 0.f, 0.f}; hpv = hpg; }
;                 if (blk < 3) { hng = *(const PG8_LAS f32x4*)(X + ((blk + 1) * 2 + 0) * 256 + cl + 4 * n); hnv = *(const PG8_LAS f32x4*)(X + ((blk + 1) * 2 + 0) * 256 + 128 + cl + 4 * n); } else { hng = (f32x4){0.f, 0.f, 0.f, 0.f}; hnv = hng; }
.LBB0_794:
	s_or_b64 exec, exec, s[12:13]
	v_lshl_add_u32 v212, s10, 7, v196
	v_ashrrev_i32_e32 v213, 31, v212
	v_lshlrev_b64 v[158:159], 2, v[212:213]
	v_lshl_add_u64 v[192:193], s[20:21], 0, v[158:159]
	v_lshl_add_u64 v[198:199], s[48:49], 0, v[158:159]
	v_lshl_add_u64 v[194:195], s[22:23], 0, v[158:159]
	v_lshl_add_u64 v[202:203], s[52:53], 0, v[158:159]
	v_lshl_add_u64 v[206:207], s[56:57], 0, v[158:159]
	v_lshl_add_u64 v[208:209], s[58:59], 0, v[158:159]
	ds_read_b128 v[114:117], v247 offset:0
	v_lshl_add_u64 v[200:201], s[50:51], 0, v[158:159]
	ds_read_b128 v[138:141], v247 offset:512
	ds_read_b128 v[134:137], v247 offset:1024
	ds_read_b128 v[154:157], v247 offset:3072
	v_lshl_add_u64 v[204:205], s[54:55], 0, v[158:159]
	ds_read_b128 v[150:153], v247 offset:1536
	ds_read_b128 v[142:145], v247 offset:2048
	ds_read_b128 v[146:149], v247 offset:2560
	ds_read_b128 v[158:161], v247 offset:3584
	v_lshlrev_b32_e32 v197, 2, v196
	v_cndmask_b32_e64 v163, 0, 1, s[40:41]
	v_add_u32_e32 v215, s84, v197
	v_add_u32_e32 v217, s91, v197
	v_mov_b32_e32 v162, 0
	v_cmp_ne_u32_e64 s[14:15], 1, v163
	s_andn2_b64 vcc, exec, s[40:41]
	v_mov_b32_e32 v170, 0
	v_mov_b32_e32 v171, 0
	v_mov_b32_e32 v172, 0
	v_mov_b32_e32 v173, 0
	v_mov_b32_e32 v174, 0
	v_mov_b32_e32 v175, 0
	v_mov_b32_e32 v176, 0
	v_mov_b32_e32 v177, 0
	s_cbranch_vccnz .LBB0_796
	ds_read_b128 v[174:177], v217
	ds_read_b128 v[170:173], v215

; __device__ __forceinline__ float fma_s(float a, float b, float c) { float d; asm("v_fma_f32 %0, %1, %2, %3" : "=v"(d) : "v"(a), "v"(b), "v"(c)); return d; }
; #define PG8_ROR1(x) dpp_ror1(x)
; #define PG8_ROR15(x) dpp_ror15(x)
;     __device__ __forceinline__ void run(f32x4 (&acc)[2][2][4][2], const Unit& un, int wr, int wc, int fr, int fq, PG8_LAS unsigned char* xl) const {
;     ...
; #pragma unroll
;                 for (int m = 0; m < 4; ++m) {
;                     float o[4];
; #pragma unroll
;                     for (int e = 0; e < 4; ++e) {
;                         const float g = acc[ai][0][m][n][e], v = acc[ai][1][m][n][e];
;                         const float gpe = m > 0 ? PG8_ROR1(acc[ai][0][m - 1][n][e]) : hpg[e], vpe = m > 0 ? PG8_ROR1(acc[ai][1][m - 1][n][e]) : hpv[e];
;                         const float gne = m < 3 ? PG8_ROR15(acc[ai][0][m + 1][n][e]) : hng[e], vne = m < 3 ? PG8_ROR15(acc[ai][1][m + 1][n][e]) : hnv[e];
;                         const float gpi = PG8_ROR1(g), vpi = PG8_ROR1(v), gni = PG8_ROR15(g), vni = PG8_ROR15(v);
;                         const float gp = e0 ? gpe : gpi, vp = e0 ? vpe : vpi, gn = e15 ? gne : gni, vn = e15 ? vne : vni;
;                         const float cg = fma_s(w2g[e], gn, fma_s(w1g[e], g, fma_s(w0g[e], gp, bg[e]))), cv = fma_s(w2v[e], vn, fma_s(w1v[e], v, fma_s(w0v[e], vp, bv[e])));
;                         o[e] = (cg * cv) * __builtin_amdgcn_rcpf(1.0f + __builtin_amdgcn_exp2f(cg * -1.4426950408889634f));
;                     }
.LBB0_798:
	v_fmamk_f32 v214, v214, 0x39800000, v244
	v_fmamk_f32 v216, v216, 0x39800000, v244
	v_rsq_f32_e32 v214, v214
	v_rsq_f32_e32 v216, v216
	v_cmp_eq_u32_e64 s[10:11], 0, v210
	v_cmp_eq_u32_e64 s[12:13], 15, v210
	v_pk_mul_f32 v[220:221], v[104:105], v[214:215] op_sel_hi:[1,0]
	v_pk_mul_f32 v[104:105], v[106:107], v[216:217] op_sel_hi:[1,0]
	v_mov_b32_dpp v106, v126 row_ror:1 row_mask:0xf bank_mask:0xf bound_ctrl:1
	s_waitcnt lgkmcnt(0)
	v_cndmask_b32_e64 v106, v106, v174, s[10:11]
	v_pk_mul_f32 v[110:111], v[110:111], v[214:215] op_sel_hi:[1,0]
	s_waitcnt lgkmcnt(0)
	v_fma_f32 v106, v114, v106, v154
	v_pk_mul_f32 v[218:219], v[102:103], v[214:215] op_sel_hi:[1,0]
	v_pk_mul_f32 v[102:103], v[108:109], v[216:217] op_sel_hi:[1,0]
	v_mov_b32_dpp v107, v130 row_ror:1 row_mask:0xf bank_mask:0xf bound_ctrl:1
	v_mov_b32_dpp v108, v126 row_ror:15 row_mask:0xf bank_mask:0xf bound_ctrl:1
	v_mov_b32_dpp v222, v110 row_ror:15 row_mask:0xf bank_mask:0xf bound_ctrl:1
	v_fma_f32 v106, v138, v126, v106
	v_cndmask_b32_e64 v107, v107, v170, s[10:11]
	v_cndmask_b32_e64 v108, v108, v222, s[12:13]
	v_fma_f32 v174, v134, v108, v106
	v_fma_f32 v106, v150, v107, v158
	v_mov_b32_dpp v109, v130 row_ror:15 row_mask:0xf bank_mask:0xf bound_ctrl:1
	v_mov_b32_dpp v223, v218 row_ror:15 row_mask:0xf bank_mask:0xf bound_ctrl:1
	v_fma_f32 v106, v142, v130, v106
	v_cndmask_b32_e64 v109, v109, v223, s[12:13]
	v_fma_f32 v224, v146, v109, v106
	v_mov_b32_dpp v107, v131 row_ror:1 row_mask:0xf bank_mask:0xf bound_ctrl:1
	v_mov_b32_dpp v106, v127 row_ror:1 row_mask:0xf bank_mask:0xf bound_ctrl:1
	v_cndmask_b32_e64 v106, v106, v175, s[10:11]
	v_fma_f32 v106, v115, v106, v155
	v_mov_b32_dpp v108, v127 row_ror:15 row_mask:0xf bank_mask:0xf bound_ctrl:1
	v_mov_b32_dpp v226, v111 row_ror:15 row_mask:0xf bank_mask:0xf bound_ctrl:1
	v_fma_f32 v106, v139, v127, v106
	v_cndmask_b32_e64 v107, v107, v171, s[10:11]
	v_cndmask_b32_e64 v108, v108, v226, s[12:13]
	v_fma_f32 v175, v135, v108, v106
	v_fma_f32 v106, v151, v107, v159
	v_mov_b32_dpp v109, v131 row_ror:15 row_mask:0xf bank_mask:0xf bound_ctrl:1
	v_mov_b32_dpp v227, v219 row_ror:15 row_mask:0xf bank_mask:0xf bound_ctrl:1
	v_fma_f32 v106, v143, v131, v106
	v_cndmask_b32_e64 v109, v109, v227, s[12:13]
	v_fma_f32 v225, v147, v109, v106
	v_pk_mul_f32 v[112:113], v[112:113], v[214:215] op_sel_hi:[1,0]
	v_mov_b32_dpp v106, v128 row_ror:1 row_mask:0xf bank_mask:0xf bound_ctrl:1
	v_cndmask_b32_e64 v106, v106, v176, s[10:11]
	v_mov_b32_dpp v107, v132 row_ror:1 row_mask:0xf bank_mask:0xf bound_ctrl:1
	v_fma_f32 v106, v116, v106, v156
	v_mov_b32_dpp v108, v128 row_ror:15 row_mask:0xf bank_mask:0xf bound_ctrl:1
	v_cndmask_b32_e64 v107, v107, v172, s[10:11]
	v_mov_b32_dpp v172, v112 row_ror:15 row_mask:0xf bank_mask:0xf bound_ctrl:1
	v_fma_f32 v106, v140, v128, v106
	v_cndmask_b32_e64 v108, v108, v172, s[12:13]
	v_fma_f32 v170, v136, v108, v106
	v_fma_f32 v106, v152, v107, v160
	v_mov_b32_dpp v109, v132 row_ror:15 row_mask:0xf bank_mask:0xf bound_ctrl:1
	v_mov_b32_dpp v230, v220 row_ror:15 row_mask:0xf bank_mask:0xf bound_ctrl:1
	v_fma_f32 v106, v144, v132, v106
	v_cndmask_b32_e64 v109, v109, v230, s[12:13]
	v_fma_f32 v176, v148, v109, v106
	v_mov_b32_dpp v107, v133 row_ror:1 row_mask:0xf bank_mask:0xf bound_ctrl:1
	v_mov_b32_dpp v106, v129 row_ror:1 row_mask:0xf bank_mask:0xf bound_ctrl:1
	v_cndmask_b32_e64 v106, v106, v177, s[10:11]
	v_fma_f32 v106, v117, v106, v157
	v_mov_b32_dpp v108, v129 row_ror:15 row_mask:0xf bank_mask:0xf bound_ctrl:1
	v_cndmask_b32_e64 v107, v107, v173, s[10:11]
	v_mov_b32_dpp v173, v113 row_ror:15 row_mask:0xf bank_mask:0xf bound_ctrl:1
	v_fma_f32 v106, v141, v129, v106
	v_cndmask_b32_e64 v108, v108, v173, s[12:13]
	v_fma_f32 v171, v137, v108, v106
	v_fma_f32 v106, v153, v107, v161
	v_mov_b32_dpp v109, v133 row_ror:15 row_mask:0xf bank_mask:0xf bound_ctrl:1
	v_mov_b32_dpp v231, v221 row_ror:15 row_mask:0xf bank_mask:0xf bound_ctrl:1
	v_fma_f32 v106, v145, v133, v106
	v_cndmask_b32_e64 v109, v109, v231, s[12:13]
	v_fma_f32 v177, v149, v109, v106
	v_mov_b32_dpp v108, v110 row_ror:1 row_mask:0xf bank_mask:0xf bound_ctrl:1
	v_mov_b32_dpp v106, v126 row_ror:1 row_mask:0xf bank_mask:0xf bound_ctrl:1
	v_cndmask_b32_e64 v106, v108, v106, s[10:11]
	v_fma_f32 v106, v114, v106, v154
	v_mov_b32_dpp v107, v130 row_ror:1 row_mask:0xf bank_mask:0xf bound_ctrl:1
	v_mov_b32_dpp v109, v218 row_ror:1 row_mask:0xf bank_mask:0xf bound_ctrl:1
	v_mov_b32_dpp v126, v104 row_ror:15 row_mask:0xf bank_mask:0xf bound_ctrl:1
	v_fma_f32 v106, v138, v110, v106
	v_pk_mul_f32 v[98:99], v[98:99], v[216:217] op_sel_hi:[1,0]
	v_cndmask_b32_e64 v107, v109, v107, s[10:11]
	v_cndmask_b32_e64 v130, v222, v126, s[12:13]
	v_fma_f32 v228, v134, v130, v106
	v_fma_f32 v106, v150, v107, v158
	v_mov_b32_dpp v222, v98 row_ror:15 row_mask:0xf bank_mask:0xf bound_ctrl:1
	v_fma_f32 v106, v142, v218, v106
	v_cndmask_b32_e64 v223, v223, v222, s[12:13]
	v_fma_f32 v234, v146, v223, v106
	v_mov_b32_dpp v110, v111 row_ror:1 row_mask:0xf bank_mask:0xf bound_ctrl:1
	v_mov_b32_dpp v106, v127 row_ror:1 row_mask:0xf bank_mask:0xf bound_ctrl:1
	v_cndmask_b32_e64 v106, v110, v106, s[10:11]
	v_fma_f32 v106, v115, v106, v155
	v_mov_b32_dpp v107, v131 row_ror:1 row_mask:0xf bank_mask:0xf bound_ctrl:1
	v_mov_b32_dpp v127, v219 row_ror:1 row_mask:0xf bank_mask:0xf bound_ctrl:1
	v_mov_b32_dpp v130, v105 row_ror:15 row_mask:0xf bank_mask:0xf bound_ctrl:1
	v_fma_f32 v106, v139, v111, v106
	v_cndmask_b32_e64 v107, v127, v107, s[10:11]
	v_cndmask_b32_e64 v131, v226, v130, s[12:13]
	v_fma_f32 v229, v135, v131, v106
	v_fma_f32 v106, v151, v107, v159
; __device__ __forceinline__ float fma_s(float a, float b, float c) { float d; asm("v_fma_f32 %0, %1, %2, %3" : "=v"(d) : "v"(a), "v"(b), "v"(c)); return d; }
; #define PG8_ROR1(x) dpp_ror1(x)
; #define PG8_ROR15(x) dpp_ror15(x)
;     __device__ __forceinline__ void run(f32x4 (&acc)[2][2][4][2], const Unit& un, int wr, int wc, int fr, int fq, PG8_LAS unsigned char* xl) const {
;     ...
;                     for (int e = 0; e < 4; ++e) {
;                         const float g = acc[ai][0][m][n][e], v = acc[ai][1][m][n][e];
;                         const float gpe = m > 0 ? PG8_ROR1(acc[ai][0][m - 1][n][e]) : hpg[e], vpe = m > 0 ? PG8_ROR1(acc[ai][1][m - 1][n][e]) : hpv[e];
;                         const float gne = m < 3 ? PG8_ROR15(acc[ai][0][m + 1][n][e]) : hng[e], vne = m < 3 ? PG8_ROR15(acc[ai][1][m + 1][n][e]) : hnv[e];
;                         const float gpi = PG8_ROR1(g), vpi = PG8_ROR1(v), gni = PG8_ROR15(g), vni = PG8_ROR15(v);
;                         const float gp = e0 ? gpe : gpi, vp = e0 ? vpe : vpi, gn = e15 ? gne : gni, vn = e15 ? vne : vni;
;                         const float cg = fma_s(w2g[e], gn, fma_s(w1g[e], g, fma_s(w0g[e], gp, bg[e]))), cv = fma_s(w2v[e], vn, fma_s(w1v[e], v, fma_s(w0v[e], vp, bv[e])));
;                         o[e] = (cg * cv) * __builtin_amdgcn_rcpf(1.0f + __builtin_amdgcn_exp2f(cg * -1.4426950408889634f));
;                     }
	v_mov_b32_dpp v223, v99 row_ror:15 row_mask:0xf bank_mask:0xf bound_ctrl:1
	v_fma_f32 v106, v143, v219, v106
	v_cndmask_b32_e64 v218, v227, v223, s[12:13]
	v_fma_f32 v235, v147, v218, v106
	v_mov_b32_dpp v111, v112 row_ror:1 row_mask:0xf bank_mask:0xf bound_ctrl:1
	v_mov_b32_dpp v106, v128 row_ror:1 row_mask:0xf bank_mask:0xf bound_ctrl:1
	v_cndmask_b32_e64 v106, v111, v106, s[10:11]
	v_fma_f32 v106, v116, v106, v156
	v_mov_b32_dpp v107, v132 row_ror:1 row_mask:0xf bank_mask:0xf bound_ctrl:1
	v_mov_b32_dpp v128, v220 row_ror:1 row_mask:0xf bank_mask:0xf bound_ctrl:1
	v_mov_b32_dpp v131, v102 row_ror:15 row_mask:0xf bank_mask:0xf bound_ctrl:1
	v_fma_f32 v106, v140, v112, v106
	v_pk_mul_f32 v[100:101], v[100:101], v[216:217] op_sel_hi:[1,0]
	v_cndmask_b32_e64 v107, v128, v107, s[10:11]
	v_cndmask_b32_e64 v132, v172, v131, s[12:13]
	v_fma_f32 v218, v136, v132, v106
	v_fma_f32 v106, v152, v107, v160
	v_mov_b32_dpp v172, v100 row_ror:15 row_mask:0xf bank_mask:0xf bound_ctrl:1
	v_fma_f32 v106, v144, v220, v106
	v_cndmask_b32_e64 v219, v230, v172, s[12:13]
	v_fma_f32 v226, v148, v219, v106
	v_mov_b32_dpp v112, v113 row_ror:1 row_mask:0xf bank_mask:0xf bound_ctrl:1
	v_mov_b32_dpp v106, v129 row_ror:1 row_mask:0xf bank_mask:0xf bound_ctrl:1
	v_cndmask_b32_e64 v106, v112, v106, s[10:11]
	v_fma_f32 v106, v117, v106, v157
	v_mov_b32_dpp v107, v133 row_ror:1 row_mask:0xf bank_mask:0xf bound_ctrl:1
	v_mov_b32_dpp v129, v221 row_ror:1 row_mask:0xf bank_mask:0xf bound_ctrl:1
	v_mov_b32_dpp v132, v103 row_ror:15 row_mask:0xf bank_mask:0xf bound_ctrl:1
	v_fma_f32 v106, v141, v113, v106
	v_cndmask_b32_e64 v107, v129, v107, s[10:11]
	v_cndmask_b32_e64 v133, v173, v132, s[12:13]
	v_fma_f32 v219, v137, v133, v106
	v_fma_f32 v106, v153, v107, v161
	v_mov_b32_dpp v113, v104 row_ror:1 row_mask:0xf bank_mask:0xf bound_ctrl:1
	v_mov_b32_dpp v173, v101 row_ror:15 row_mask:0xf bank_mask:0xf bound_ctrl:1
	v_fma_f32 v106, v145, v221, v106
	v_cndmask_b32_e64 v108, v113, v108, s[10:11]
	v_cndmask_b32_e64 v220, v231, v173, s[12:13]
	v_fma_f32 v227, v149, v220, v106
	v_mov_b32_dpp v106, v118 row_ror:15 row_mask:0xf bank_mask:0xf bound_ctrl:1
	v_mov_b32_dpp v133, v98 row_ror:1 row_mask:0xf bank_mask:0xf bound_ctrl:1
	v_fma_f32 v108, v114, v108, v154
	v_mov_b32_dpp v107, v122 row_ror:15 row_mask:0xf bank_mask:0xf bound_ctrl:1
	v_fma_f32 v104, v138, v104, v108
	v_cndmask_b32_e64 v109, v133, v109, s[10:11]
	v_cndmask_b32_e64 v106, v126, v106, s[12:13]
	v_fma_f32 v232, v134, v106, v104
	v_fma_f32 v104, v150, v109, v158
	v_cndmask_b32_e64 v107, v222, v107, s[12:13]
	v_fma_f32 v98, v142, v98, v104
	s_nop 0
	v_fma_f32 v236, v146, v107, v98
	v_mov_b32_dpp v106, v105 row_ror:1 row_mask:0xf bank_mask:0xf bound_ctrl:1
	v_mov_b32_dpp v98, v119 row_ror:15 row_mask:0xf bank_mask:0xf bound_ctrl:1
	v_mov_b32_dpp v107, v99 row_ror:1 row_mask:0xf bank_mask:0xf bound_ctrl:1
	v_cndmask_b32_e64 v108, v106, v110, s[10:11]
	v_cndmask_b32_e64 v98, v130, v98, s[12:13]
	v_mov_b32_dpp v104, v123 row_ror:15 row_mask:0xf bank_mask:0xf bound_ctrl:1
	v_cndmask_b32_e64 v109, v107, v127, s[10:11]
	v_fma_f32 v108, v115, v108, v155
	v_cndmask_b32_e64 v104, v223, v104, s[12:13]
	v_fma_f32 v105, v139, v105, v108
	s_nop 0
	v_fma_f32 v233, v135, v98, v105
	v_fma_f32 v98, v151, v109, v159
	s_nop 0
	v_fma_f32 v98, v143, v99, v98
	v_mov_b32_dpp v99, v124 row_ror:15 row_mask:0xf bank_mask:0xf bound_ctrl:1
	v_fma_f32 v237, v147, v104, v98
	v_mov_b32_dpp v104, v102 row_ror:1 row_mask:0xf bank_mask:0xf bound_ctrl:1
	v_mov_b32_dpp v98, v120 row_ror:15 row_mask:0xf bank_mask:0xf bound_ctrl:1
	v_mov_b32_dpp v105, v100 row_ror:1 row_mask:0xf bank_mask:0xf bound_ctrl:1
	v_cndmask_b32_e64 v108, v104, v111, s[10:11]
	v_cndmask_b32_e64 v98, v131, v98, s[12:13]
	v_cndmask_b32_e64 v109, v105, v128, s[10:11]
	v_cndmask_b32_e64 v99, v172, v99, s[12:13]
	v_fma_f32 v108, v116, v108, v156
	s_nop 0
	v_fma_f32 v102, v140, v102, v108
	s_nop 0
	v_fma_f32 v172, v136, v98, v102
	v_fma_f32 v98, v152, v109, v160
	s_nop 0
	v_fma_f32 v98, v144, v100, v98
	v_mov_b32_dpp v100, v103 row_ror:1 row_mask:0xf bank_mask:0xf bound_ctrl:1
	v_fma_f32 v220, v148, v99, v98
	v_mov_b32_dpp v99, v125 row_ror:15 row_mask:0xf bank_mask:0xf bound_ctrl:1
	v_mov_b32_dpp v98, v121 row_ror:15 row_mask:0xf bank_mask:0xf bound_ctrl:1
; #define PG8_LAS __attribute__((address_space(3)))
; #define PG8_GAS __attribute__((address_space(1)))
; #define PG8_ROR1(x) dpp_ror1(x)
;     __device__ __forceinline__ void run(f32x4 (&acc)[2][2][4][2], const Unit& un, int wr, int wc, int fr, int fq, PG8_LAS unsigned char* xl) const {
;     ...
;             for (int n = 0; n < 2; ++n) {
;                 const int j = un.pn * 128 + cl + 4 * n;
;                 const f32x4 w0g = *(const PG8_GAS f32x4*)(cw + j), w1g = *(const PG8_GAS f32x4*)(cw + nup + j), w2g = *(const PG8_GAS f32x4*)(cw + 2 * (size_t)nup + j), bg = *(const PG8_GAS f32x4*)(cb + j);
;                 const f32x4 w0v = *(const PG8_GAS f32x4*)(cw + dff + j), w1v = *(const PG8_GAS f32x4*)(cw + nup + dff + j), w2v = *(const PG8_GAS f32x4*)(cw + 2 * (size_t)nup + dff + j), bv = *(const PG8_GAS f32x4*)(cb + dff + j);
;                 f32x4 hpg, hpv, hng, hnv;
;                 if (blk > 0) { hpg = *(const PG8_LAS f32x4*)(X + ((blk - 1) * 2 + 1) * 256 + cl + 4 * n); hpv = *(const PG8_LAS f32x4*)(X + ((blk - 1) * 2 + 1) * 256 + 128 + cl + 4 * n); } else { hpg = (f32x4){0.f, 0.f, 0.f, 0.f}; hpv = hpg; }
;                 if (blk < 3) { hng = *(const PG8_LAS f32x4*)(X + ((blk + 1) * 2 + 0) * 256 + cl + 4 * n); hnv = *(const PG8_LAS f32x4*)(X + ((blk + 1) * 2 + 0) * 256 + 128 + cl + 4 * n); } else { hng = (f32x4){0.f, 0.f, 0.f, 0.f}; hnv = hng; }
;     ...
;                     for (int e = 0; e < 4; ++e) {
;                         const float g = acc[ai][0][m][n][e], v = acc[ai][1][m][n][e];
;                         const float gpe = m > 0 ? PG8_ROR1(acc[ai][0][m - 1][n][e]) : hpg[e], vpe = m > 0 ? PG8_ROR1(acc[ai][1][m - 1][n][e]) : hpv[e];
;                         const float gne = m < 3 ? PG8_ROR15(acc[ai][0][m + 1][n][e]) : hng[e], vne = m < 3 ? PG8_ROR15(acc[ai][1][m + 1][n][e]) : hnv[e];
;                         const float gpi = PG8_ROR1(g), vpi = PG8_ROR1(v), gni = PG8_ROR15(g), vni = PG8_ROR15(v);
;                         const float gp = e0 ? gpe : gpi, vp = e0 ? vpe : vpi, gn = e15 ? gne : gni, vn = e15 ? vne : vni;
;                         const float cg = fma_s(w2g[e], gn, fma_s(w1g[e], g, fma_s(w0g[e], gp, bg[e]))), cv = fma_s(w2v[e], vn, fma_s(w1v[e], v, fma_s(w0v[e], vp, bv[e])));
;                         o[e] = (cg * cv) * __builtin_amdgcn_rcpf(1.0f + __builtin_amdgcn_exp2f(cg * -1.4426950408889634f));
;                     }
	v_mov_b32_dpp v102, v101 row_ror:1 row_mask:0xf bank_mask:0xf bound_ctrl:1
	v_cndmask_b32_e64 v108, v100, v112, s[10:11]
	v_cndmask_b32_e64 v98, v132, v98, s[12:13]
	v_cndmask_b32_e64 v109, v102, v129, s[10:11]
	v_cndmask_b32_e64 v99, v173, v99, s[12:13]
	v_fma_f32 v108, v117, v108, v157
	s_nop 0
	v_fma_f32 v103, v141, v103, v108
	s_nop 0
	v_fma_f32 v173, v137, v98, v103
	v_fma_f32 v98, v153, v109, v161
	s_nop 0
	v_fma_f32 v98, v145, v101, v98
	v_mov_b32_dpp v101, v118 row_ror:15 row_mask:0xf bank_mask:0xf bound_ctrl:1
	v_fma_f32 v221, v149, v99, v98
	v_mov_b32_dpp v99, v122 row_ror:1 row_mask:0xf bank_mask:0xf bound_ctrl:1
	v_mov_b32_dpp v98, v118 row_ror:1 row_mask:0xf bank_mask:0xf bound_ctrl:1
	v_cndmask_b32_e64 v98, v98, v113, s[10:11]
	v_fma_f32 v98, v114, v98, v154
	v_cndmask_b32_e64 v99, v99, v133, s[10:11]
	v_fma_f32 v98, v138, v118, v98
	v_cndmask_b32_e64 v101, v101, v166, s[12:13]
	v_fma_f32 v222, v134, v101, v98
	v_fma_f32 v98, v150, v99, v158
	v_mov_b32_dpp v103, v122 row_ror:15 row_mask:0xf bank_mask:0xf bound_ctrl:1
	v_fma_f32 v98, v142, v122, v98
	v_cndmask_b32_e64 v103, v103, v162, s[12:13]
	v_fma_f32 v230, v146, v103, v98
	v_mov_b32_dpp v99, v123 row_ror:1 row_mask:0xf bank_mask:0xf bound_ctrl:1
	v_mov_b32_dpp v98, v119 row_ror:1 row_mask:0xf bank_mask:0xf bound_ctrl:1
	v_cndmask_b32_e64 v98, v98, v106, s[10:11]
	v_fma_f32 v98, v115, v98, v155
	v_mov_b32_dpp v101, v119 row_ror:15 row_mask:0xf bank_mask:0xf bound_ctrl:1
	v_fma_f32 v98, v139, v119, v98
	v_cndmask_b32_e64 v99, v99, v107, s[10:11]
	v_cndmask_b32_e64 v101, v101, v167, s[12:13]
	v_fma_f32 v223, v135, v101, v98
	v_fma_f32 v98, v151, v99, v159
	v_mov_b32_dpp v103, v123 row_ror:15 row_mask:0xf bank_mask:0xf bound_ctrl:1
	v_fma_f32 v98, v143, v123, v98
	v_cndmask_b32_e64 v103, v103, v163, s[12:13]
	v_fma_f32 v231, v147, v103, v98
	v_mov_b32_dpp v99, v124 row_ror:1 row_mask:0xf bank_mask:0xf bound_ctrl:1
	v_mov_b32_dpp v98, v120 row_ror:1 row_mask:0xf bank_mask:0xf bound_ctrl:1
	v_cndmask_b32_e64 v98, v98, v104, s[10:11]
	v_fma_f32 v98, v116, v98, v156
	v_mov_b32_dpp v101, v120 row_ror:15 row_mask:0xf bank_mask:0xf bound_ctrl:1
	v_fma_f32 v98, v140, v120, v98
	v_cndmask_b32_e64 v99, v99, v105, s[10:11]
	v_cndmask_b32_e64 v101, v101, v168, s[12:13]
	v_fma_f32 v138, v136, v101, v98
	v_fma_f32 v98, v152, v99, v160
	v_mov_b32_dpp v103, v124 row_ror:15 row_mask:0xf bank_mask:0xf bound_ctrl:1
	v_fma_f32 v98, v144, v124, v98
	v_cndmask_b32_e64 v103, v103, v164, s[12:13]
	v_fma_f32 v154, v148, v103, v98
	v_mov_b32_dpp v99, v125 row_ror:1 row_mask:0xf bank_mask:0xf bound_ctrl:1
	v_mov_b32_dpp v98, v121 row_ror:1 row_mask:0xf bank_mask:0xf bound_ctrl:1
	v_cndmask_b32_e64 v98, v98, v100, s[10:11]
	v_fma_f32 v98, v117, v98, v157
	v_mov_b32_dpp v101, v121 row_ror:15 row_mask:0xf bank_mask:0xf bound_ctrl:1
	v_mov_b32_dpp v103, v125 row_ror:15 row_mask:0xf bank_mask:0xf bound_ctrl:1
	v_fma_f32 v98, v141, v121, v98
	v_cndmask_b32_e64 v99, v99, v102, s[10:11]
	v_cndmask_b32_e64 v100, v101, v169, s[12:13]
	v_cndmask_b32_e64 v101, v103, v165, s[12:13]
	v_fma_f32 v139, v137, v100, v98
	v_fma_f32 v98, v153, v99, v161
	s_nop 0
	v_fma_f32 v98, v145, v125, v98
	s_nop 0
	v_fma_f32 v155, v149, v101, v98
	v_or_b32_e32 v102, 4, v212
	v_ashrrev_i32_e32 v103, 31, v102
	v_lshlrev_b64 v[126:127], 2, v[102:103]
	v_lshl_add_u64 v[156:157], s[48:49], 0, v[126:127]
	ds_read_b128 v[98:101], v247 offset:16
	v_lshl_add_u64 v[158:159], s[50:51], 0, v[126:127]
	ds_read_b128 v[106:109], v247 offset:528
	ds_read_b128 v[102:105], v247 offset:1040
	ds_read_b128 v[118:121], v247 offset:3088
	v_lshl_add_u64 v[160:161], s[52:53], 0, v[126:127]
	v_lshl_add_u64 v[164:165], s[56:57], 0, v[126:127]
	v_lshl_add_u64 v[166:167], s[58:59], 0, v[126:127]
	v_lshl_add_u64 v[162:163], s[54:55], 0, v[126:127]
	ds_read_b128 v[110:113], v247 offset:1552
	ds_read_b128 v[114:117], v247 offset:2064
	ds_read_b128 v[122:125], v247 offset:2576
	ds_read_b128 v[126:129], v247 offset:3600
	v_mov_b32_e32 v130, 0
	s_and_b64 vcc, exec, s[14:15]
	v_mov_b32_e32 v144, 0
	v_mov_b32_e32 v145, 0
	v_mov_b32_e32 v146, 0
	v_mov_b32_e32 v147, 0
	v_mov_b32_e32 v148, 0
	v_mov_b32_e32 v149, 0
	v_mov_b32_e32 v150, 0
	v_mov_b32_e32 v151, 0
	s_cbranch_vccnz .LBB0_800
	ds_read_b128 v[148:151], v217 offset:16
	ds_read_b128 v[144:147], v215 offset:16

; #define PG8_GAS __attribute__((address_space(1)))
; __device__ __forceinline__ unsigned cvt_pk_bf16(float lo, float hi) { const f32x2c v = {lo, hi}; return __builtin_bit_cast(unsigned, __builtin_convertvector(v, bf16x2c)); }
; __device__ __forceinline__ float fma_s(float a, float b, float c) { float d; asm("v_fma_f32 %0, %1, %2, %3" : "=v"(d) : "v"(a), "v"(b), "v"(c)); return d; }
; #define PG8_ROR1(x) dpp_ror1(x)
; #define PG8_ROR15(x) dpp_ror15(x)
;     __device__ __forceinline__ void run(f32x4 (&acc)[2][2][4][2], const Unit& un, int wr, int wc, int fr, int fq, PG8_LAS unsigned char* xl) const {
;     ...
;                 for (int m = 0; m < 4; ++m) {
;                     float o[4];
; #pragma unroll
;                     for (int e = 0; e < 4; ++e) {
;                         const float g = acc[ai][0][m][n][e], v = acc[ai][1][m][n][e];
;                         const float gpe = m > 0 ? PG8_ROR1(acc[ai][0][m - 1][n][e]) : hpg[e], vpe = m > 0 ? PG8_ROR1(acc[ai][1][m - 1][n][e]) : hpv[e];
;                         const float gne = m < 3 ? PG8_ROR15(acc[ai][0][m + 1][n][e]) : hng[e], vne = m < 3 ? PG8_ROR15(acc[ai][1][m + 1][n][e]) : hnv[e];
;                         const float gpi = PG8_ROR1(g), vpi = PG8_ROR1(v), gni = PG8_ROR15(g), vni = PG8_ROR15(v);
;                         const float gp = e0 ? gpe : gpi, vp = e0 ? vpe : vpi, gn = e15 ? gne : gni, vn = e15 ? vne : vni;
;                         const float cg = fma_s(w2g[e], gn, fma_s(w1g[e], g, fma_s(w0g[e], gp, bg[e]))), cv = fma_s(w2v[e], vn, fma_s(w1v[e], v, fma_s(w0v[e], vp, bv[e])));
;                         o[e] = (cg * cv) * __builtin_amdgcn_rcpf(1.0f + __builtin_amdgcn_exp2f(cg * -1.4426950408889634f));
;                     }
;                     if (n == 0) { keep[m].x = cvt_pk_bf16(o[0], o[1]); keep[m].y = cvt_pk_bf16(o[2], o[3]); }
;                     else { u32x4 w; w.x = keep[m].x; w.y = keep[m].y; w.z = cvt_pk_bf16(o[0], o[1]); w.w = cvt_pk_bf16(o[2], o[3]);
;                         *(PG8_GAS u32x4*)(act + (size_t)(row0 + ai * HALF + m * 16) * dff + j - 4) = w; }
.LBB0_802:
	v_mul_f32_e32 v140, 0xbfb8aa3b, v174
	v_mul_f32_e32 v141, 0xbfb8aa3b, v175
	v_exp_f32_e32 v140, v140
	v_exp_f32_e32 v141, v141
	v_pk_mul_f32 v[142:143], v[174:175], v[224:225]
	v_pk_mul_f32 v[152:153], v[170:171], v[176:177]
	v_add_f32_e32 v140, 1.0, v140
	v_add_f32_e32 v141, 1.0, v141
	v_rcp_f32_e32 v140, v140
	v_rcp_f32_e32 v141, v141
	v_pk_mul_f32 v[168:169], v[218:219], v[226:227]
	v_mov_b32_e32 v215, v214
	v_mov_b32_e32 v217, v216
	v_pk_mul_f32 v[140:141], v[142:143], v[140:141]
	v_mul_f32_e32 v142, 0xbfb8aa3b, v170
	v_mul_f32_e32 v143, 0xbfb8aa3b, v171
	v_exp_f32_e32 v142, v142
	v_exp_f32_e32 v143, v143
	v_pk_mul_f32 v[170:171], v[172:173], v[220:221]
	s_lshl_b32 s14, s76, 8
	v_add_f32_e32 v142, 1.0, v142
	v_add_f32_e32 v143, 1.0, v143
	v_rcp_f32_e32 v142, v142
	v_rcp_f32_e32 v143, v143
	s_add_i32 s14, s14, s34
	v_pk_mul_f32 v[142:143], v[152:153], v[142:143]
	v_cvt_pk_bf16_f32 v152, v140, v141
	v_mul_f32_e32 v140, 0xbfb8aa3b, v228
	v_mul_f32_e32 v141, 0xbfb8aa3b, v229
	v_exp_f32_e32 v140, v140
	v_exp_f32_e32 v141, v141
	v_cvt_pk_bf16_f32 v153, v142, v143
	v_pk_mul_f32 v[142:143], v[228:229], v[234:235]
	v_add_f32_e32 v140, 1.0, v140
	v_add_f32_e32 v141, 1.0, v141
	v_rcp_f32_e32 v140, v140
	v_rcp_f32_e32 v141, v141
	s_nop 0
	v_pk_mul_f32 v[140:141], v[142:143], v[140:141]
	v_mul_f32_e32 v142, 0xbfb8aa3b, v218
	v_mul_f32_e32 v143, 0xbfb8aa3b, v219
	v_exp_f32_e32 v142, v142
	v_exp_f32_e32 v143, v143
	v_add_f32_e32 v142, 1.0, v142
	v_add_f32_e32 v143, 1.0, v143
	v_rcp_f32_e32 v142, v142
	v_rcp_f32_e32 v143, v143
	s_nop 0
	v_pk_mul_f32 v[168:169], v[168:169], v[142:143]
	v_cvt_pk_bf16_f32 v142, v140, v141
	v_mul_f32_e32 v140, 0xbfb8aa3b, v232
	v_mul_f32_e32 v141, 0xbfb8aa3b, v233
	v_exp_f32_e32 v140, v140
	v_exp_f32_e32 v141, v141
	v_cvt_pk_bf16_f32 v143, v168, v169
	v_pk_mul_f32 v[168:169], v[232:233], v[236:237]
	v_add_f32_e32 v140, 1.0, v140
	v_add_f32_e32 v141, 1.0, v141
	v_rcp_f32_e32 v140, v140
	v_rcp_f32_e32 v141, v141
	s_nop 0
	v_pk_mul_f32 v[140:141], v[168:169], v[140:141]
	v_mul_f32_e32 v168, 0xbfb8aa3b, v172
	v_mul_f32_e32 v169, 0xbfb8aa3b, v173
	v_exp_f32_e32 v168, v168
	v_exp_f32_e32 v169, v169
	v_cvt_pk_bf16_f32 v140, v140, v141
	v_add_u32_e32 v172, s14, v210
	v_add_f32_e32 v168, 1.0, v168
	v_add_f32_e32 v169, 1.0, v169
	v_rcp_f32_e32 v168, v168
	v_rcp_f32_e32 v169, v169
	s_nop 0
	v_pk_mul_f32 v[168:169], v[170:171], v[168:169]
	s_nop 0
	v_cvt_pk_bf16_f32 v141, v168, v169
	v_mul_f32_e32 v168, 0xbfb8aa3b, v222
	v_mul_f32_e32 v169, 0xbfb8aa3b, v223
	v_exp_f32_e32 v168, v168
	v_exp_f32_e32 v169, v169
	v_pk_mul_f32 v[170:171], v[222:223], v[230:231]
	v_add_f32_e32 v168, 1.0, v168
	v_add_f32_e32 v169, 1.0, v169
	v_rcp_f32_e32 v168, v168
	v_rcp_f32_e32 v169, v169
	s_nop 0
	v_pk_mul_f32 v[168:169], v[170:171], v[168:169]
	v_mul_f32_e32 v170, 0xbfb8aa3b, v138
	v_mul_f32_e32 v171, 0xbfb8aa3b, v139
	v_exp_f32_e32 v170, v170
	v_exp_f32_e32 v171, v171
	v_pk_mul_f32 v[138:139], v[138:139], v[154:155]
	v_add_f32_e32 v170, 1.0, v170
	v_add_f32_e32 v171, 1.0, v171
	v_rcp_f32_e32 v170, v170
	v_rcp_f32_e32 v171, v171
	s_nop 0
	v_pk_mul_f32 v[154:155], v[138:139], v[170:171]
	s_nop 0
	v_cvt_pk_bf16_f32 v139, v154, v155
	v_mov_b32_e32 v154, v214
	v_mov_b32_e32 v155, v214
	v_cvt_pk_bf16_f32 v138, v168, v169
	v_pk_mul_f32 v[168:169], v[86:87], v[214:215]
	v_pk_mul_f32 v[86:87], v[80:81], v[154:155]
	v_pk_mul_f32 v[80:81], v[82:83], v[216:217]
	v_pk_mul_f32 v[82:83], v[74:75], v[216:217]
	v_mov_b32_dpp v74, v90 row_ror:1 row_mask:0xf bank_mask:0xf bound_ctrl:1
	v_mov_b32_dpp v75, v94 row_ror:1 row_mask:0xf bank_mask:0xf bound_ctrl:1
	v_pk_mul_f32 v[88:89], v[88:89], v[154:155]
	v_mov_b32_e32 v154, v216
	v_mov_b32_e32 v155, v216
	s_waitcnt lgkmcnt(1)
	v_cndmask_b32_e64 v74, v74, v148, s[10:11]
	s_waitcnt lgkmcnt(0)
	v_cndmask_b32_e64 v75, v75, v144, s[10:11]
	v_pk_mul_f32 v[170:171], v[78:79], v[214:215]
	v_pk_mul_f32 v[78:79], v[84:85], v[154:155]
	v_mov_b32_dpp v84, v90 row_ror:15 row_mask:0xf bank_mask:0xf bound_ctrl:1
	v_mov_b32_dpp v148, v168 row_ror:15 row_mask:0xf bank_mask:0xf bound_ctrl:1
	s_waitcnt lgkmcnt(0)
	v_fma_f32 v74, v98, v74, v118
	s_waitcnt lgkmcnt(0)
	v_fma_f32 v75, v110, v75, v126
	v_mov_b32_dpp v85, v94 row_ror:15 row_mask:0xf bank_mask:0xf bound_ctrl:1
	v_cndmask_b32_e64 v84, v84, v148, s[12:13]
	v_mov_b32_dpp v173, v170 row_ror:15 row_mask:0xf bank_mask:0xf bound_ctrl:1
	v_fma_f32 v74, v106, v90, v74
	v_fma_f32 v75, v114, v94, v75
	v_cndmask_b32_e64 v85, v85, v173, s[12:13]
	v_fma_f32 v74, v102, v84, v74
	v_fma_f32 v84, v122, v85, v75
	v_pk_mul_f32 v[76:77], v[76:77], v[154:155]
	v_mul_f32_e32 v75, 0xbfb8aa3b, v74
	v_exp_f32_e32 v75, v75
	v_mov_b32_dpp v85, v95 row_ror:1 row_mask:0xf bank_mask:0xf bound_ctrl:1
	v_mov_b32_dpp v154, v91 row_ror:15 row_mask:0xf bank_mask:0xf bound_ctrl:1
	v_cndmask_b32_e64 v85, v85, v145, s[10:11]
	v_add_f32_e32 v75, 1.0, v75
	v_rcp_f32_e32 v144, v75
	v_fma_f32 v85, v111, v85, v127
	v_mov_b32_dpp v155, v95 row_ror:15 row_mask:0xf bank_mask:0xf bound_ctrl:1
	v_mov_b32_dpp v75, v91 row_ror:1 row_mask:0xf bank_mask:0xf bound_ctrl:1
	v_cndmask_b32_e64 v75, v75, v149, s[10:11]
	v_mov_b32_dpp v149, v169 row_ror:15 row_mask:0xf bank_mask:0xf bound_ctrl:1
	v_fma_f32 v75, v99, v75, v119
	v_cndmask_b32_e64 v145, v154, v149, s[12:13]
	v_fma_f32 v75, v107, v91, v75
	v_mov_b32_dpp v174, v171 row_ror:15 row_mask:0xf bank_mask:0xf bound_ctrl:1
	v_fma_f32 v75, v103, v145, v75
	v_fma_f32 v85, v115, v95, v85
	v_cndmask_b32_e64 v154, v155, v174, s[12:13]
	v_mul_f32_e32 v145, 0xbfb8aa3b, v75
	v_exp_f32_e32 v145, v145
	v_fma_f32 v85, v123, v154, v85
	v_mov_b32_dpp v175, v86 row_ror:15 row_mask:0xf bank_mask:0xf bound_ctrl:1
; #define PG8_GAS __attribute__((address_space(1)))
; __device__ __forceinline__ unsigned cvt_pk_bf16(float lo, float hi) { const f32x2c v = {lo, hi}; return __builtin_bit_cast(unsigned, __builtin_convertvector(v, bf16x2c)); }
; __device__ __forceinline__ float fma_s(float a, float b, float c) { float d; asm("v_fma_f32 %0, %1, %2, %3" : "=v"(d) : "v"(a), "v"(b), "v"(c)); return d; }
; #define PG8_ROR1(x) dpp_ror1(x)
; #define PG8_ROR15(x) dpp_ror15(x)
;     __device__ __forceinline__ void run(f32x4 (&acc)[2][2][4][2], const Unit& un, int wr, int wc, int fr, int fq, PG8_LAS unsigned char* xl) const {
;     ...
;                 for (int m = 0; m < 4; ++m) {
;                     float o[4];
; #pragma unroll
;                     for (int e = 0; e < 4; ++e) {
;                         const float g = acc[ai][0][m][n][e], v = acc[ai][1][m][n][e];
;                         const float gpe = m > 0 ? PG8_ROR1(acc[ai][0][m - 1][n][e]) : hpg[e], vpe = m > 0 ? PG8_ROR1(acc[ai][1][m - 1][n][e]) : hpv[e];
;                         const float gne = m < 3 ? PG8_ROR15(acc[ai][0][m + 1][n][e]) : hng[e], vne = m < 3 ? PG8_ROR15(acc[ai][1][m + 1][n][e]) : hnv[e];
;                         const float gpi = PG8_ROR1(g), vpi = PG8_ROR1(v), gni = PG8_ROR15(g), vni = PG8_ROR15(v);
;                         const float gp = e0 ? gpe : gpi, vp = e0 ? vpe : vpi, gn = e15 ? gne : gni, vn = e15 ? vne : vni;
;                         const float cg = fma_s(w2g[e], gn, fma_s(w1g[e], g, fma_s(w0g[e], gp, bg[e]))), cv = fma_s(w2v[e], vn, fma_s(w1v[e], v, fma_s(w0v[e], vp, bv[e])));
;                         o[e] = (cg * cv) * __builtin_amdgcn_rcpf(1.0f + __builtin_amdgcn_exp2f(cg * -1.4426950408889634f));
;                     }
;                     if (n == 0) { keep[m].x = cvt_pk_bf16(o[0], o[1]); keep[m].y = cvt_pk_bf16(o[2], o[3]); }
;                     else { u32x4 w; w.x = keep[m].x; w.y = keep[m].y; w.z = cvt_pk_bf16(o[0], o[1]); w.w = cvt_pk_bf16(o[2], o[3]);
;                         *(PG8_GAS u32x4*)(act + (size_t)(row0 + ai * HALF + m * 16) * dff + j - 4) = w; }
	v_pk_mul_f32 v[74:75], v[74:75], v[84:85]
	v_add_f32_e32 v145, 1.0, v145
	v_rcp_f32_e32 v145, v145
	v_mov_b32_dpp v84, v92 row_ror:1 row_mask:0xf bank_mask:0xf bound_ctrl:1
	v_mov_b32_dpp v85, v96 row_ror:1 row_mask:0xf bank_mask:0xf bound_ctrl:1
	v_cndmask_b32_e64 v84, v84, v150, s[10:11]
	v_cndmask_b32_e64 v85, v85, v146, s[10:11]
	v_pk_mul_f32 v[74:75], v[74:75], v[144:145]
	v_mov_b32_dpp v144, v92 row_ror:15 row_mask:0xf bank_mask:0xf bound_ctrl:1
	v_mov_b32_dpp v150, v88 row_ror:15 row_mask:0xf bank_mask:0xf bound_ctrl:1
	v_fma_f32 v84, v100, v84, v120
	v_fma_f32 v85, v112, v85, v128
	v_mov_b32_dpp v145, v96 row_ror:15 row_mask:0xf bank_mask:0xf bound_ctrl:1
	v_cndmask_b32_e64 v144, v144, v150, s[12:13]
	v_fma_f32 v84, v108, v92, v84
	v_fma_f32 v85, v116, v96, v85
	v_cndmask_b32_e64 v145, v145, v175, s[12:13]
	v_fma_f32 v84, v104, v144, v84
	v_fma_f32 v144, v124, v145, v85
	v_mov_b32_dpp v154, v93 row_ror:15 row_mask:0xf bank_mask:0xf bound_ctrl:1
	v_mul_f32_e32 v85, 0xbfb8aa3b, v84
	v_exp_f32_e32 v85, v85
	v_mov_b32_dpp v145, v97 row_ror:1 row_mask:0xf bank_mask:0xf bound_ctrl:1
	v_cndmask_b32_e64 v145, v145, v147, s[10:11]
	v_fma_f32 v145, v113, v145, v129
	v_add_f32_e32 v85, 1.0, v85
	v_rcp_f32_e32 v146, v85
	v_mov_b32_dpp v155, v97 row_ror:15 row_mask:0xf bank_mask:0xf bound_ctrl:1
	v_mov_b32_dpp v85, v93 row_ror:1 row_mask:0xf bank_mask:0xf bound_ctrl:1
	v_cndmask_b32_e64 v85, v85, v151, s[10:11]
	v_mov_b32_dpp v151, v89 row_ror:15 row_mask:0xf bank_mask:0xf bound_ctrl:1
	v_fma_f32 v85, v101, v85, v121
	v_cndmask_b32_e64 v147, v154, v151, s[12:13]
	v_fma_f32 v85, v109, v93, v85
	v_mov_b32_dpp v176, v87 row_ror:15 row_mask:0xf bank_mask:0xf bound_ctrl:1
	v_fma_f32 v85, v105, v147, v85
	v_fma_f32 v145, v117, v97, v145
	v_cndmask_b32_e64 v154, v155, v176, s[12:13]
	v_mul_f32_e32 v147, 0xbfb8aa3b, v85
	v_exp_f32_e32 v147, v147
	v_fma_f32 v145, v125, v154, v145
	v_cvt_pk_bf16_f32 v154, v74, v75
	v_pk_mul_f32 v[84:85], v[84:85], v[144:145]
	v_add_f32_e32 v147, 1.0, v147
	v_rcp_f32_e32 v147, v147
	v_mov_b64_e32 v[74:75], s[24:25]
	v_pk_mul_f32 v[84:85], v[84:85], v[146:147]
	s_nop 0
	v_cvt_pk_bf16_f32 v155, v84, v85
	v_mad_i64_i32 v[84:85], s[14:15], v172, s5, v[74:75]
	v_lshlrev_b64 v[146:147], 1, v[212:213]
	v_lshl_add_u64 v[84:85], v[84:85], 0, v[146:147]
	global_store_dwordx4 v[84:85], v[152:155], off
	s_nop 0
	v_mov_b32_dpp v84, v90 row_ror:1 row_mask:0xf bank_mask:0xf bound_ctrl:1
	v_mov_b32_dpp v85, v94 row_ror:1 row_mask:0xf bank_mask:0xf bound_ctrl:1
	v_mov_b32_dpp v152, v168 row_ror:1 row_mask:0xf bank_mask:0xf bound_ctrl:1
	v_mov_b32_dpp v153, v170 row_ror:1 row_mask:0xf bank_mask:0xf bound_ctrl:1
	v_cndmask_b32_e64 v84, v152, v84, s[10:11]
	v_cndmask_b32_e64 v85, v153, v85, s[10:11]
	v_mov_b32_dpp v154, v80 row_ror:15 row_mask:0xf bank_mask:0xf bound_ctrl:1
	v_fma_f32 v84, v98, v84, v118
	v_fma_f32 v85, v110, v85, v126
	v_cndmask_b32_e64 v90, v148, v154, s[12:13]
	v_mov_b32_dpp v148, v82 row_ror:15 row_mask:0xf bank_mask:0xf bound_ctrl:1
	v_fma_f32 v84, v106, v168, v84
	v_fma_f32 v85, v114, v170, v85
	v_cndmask_b32_e64 v94, v173, v148, s[12:13]
	v_fma_f32 v84, v102, v90, v84
	v_fma_f32 v90, v122, v94, v85
	v_mov_b32_dpp v155, v169 row_ror:1 row_mask:0xf bank_mask:0xf bound_ctrl:1
	v_mul_f32_e32 v85, 0xbfb8aa3b, v84
	v_exp_f32_e32 v85, v85
	v_mov_b32_dpp v170, v81 row_ror:15 row_mask:0xf bank_mask:0xf bound_ctrl:1
	v_mov_b32_dpp v168, v171 row_ror:1 row_mask:0xf bank_mask:0xf bound_ctrl:1
	v_add_f32_e32 v85, 1.0, v85
	v_rcp_f32_e32 v94, v85
	s_nop 0
	v_mov_b32_dpp v85, v91 row_ror:1 row_mask:0xf bank_mask:0xf bound_ctrl:1
	v_cndmask_b32_e64 v85, v155, v85, s[10:11]
	v_fma_f32 v85, v99, v85, v119
	v_mov_b32_dpp v91, v95 row_ror:1 row_mask:0xf bank_mask:0xf bound_ctrl:1
	v_cndmask_b32_e64 v95, v149, v170, s[12:13]
	v_fma_f32 v85, v107, v169, v85
	v_cndmask_b32_e64 v91, v168, v91, s[10:11]
	v_fma_f32 v85, v103, v95, v85
	v_fma_f32 v91, v111, v91, v127
	v_mov_b32_dpp v149, v83 row_ror:15 row_mask:0xf bank_mask:0xf bound_ctrl:1
	v_mul_f32_e32 v95, 0xbfb8aa3b, v85
	v_exp_f32_e32 v95, v95
	v_fma_f32 v91, v115, v171, v91
	v_cndmask_b32_e64 v144, v174, v149, s[12:13]
	v_fma_f32 v91, v123, v144, v91
	v_add_f32_e32 v95, 1.0, v95
	v_rcp_f32_e32 v95, v95
	v_pk_mul_f32 v[84:85], v[84:85], v[90:91]
	v_mov_b32_dpp v90, v92 row_ror:1 row_mask:0xf bank_mask:0xf bound_ctrl:1
	v_mov_b32_dpp v92, v88 row_ror:1 row_mask:0xf bank_mask:0xf bound_ctrl:1
	v_pk_mul_f32 v[84:85], v[84:85], v[94:95]
	v_mov_b32_dpp v91, v96 row_ror:1 row_mask:0xf bank_mask:0xf bound_ctrl:1
	v_mov_b32_dpp v94, v86 row_ror:1 row_mask:0xf bank_mask:0xf bound_ctrl:1
	v_cndmask_b32_e64 v90, v92, v90, s[10:11]
	v_mov_b32_dpp v95, v78 row_ror:15 row_mask:0xf bank_mask:0xf bound_ctrl:1
	v_cndmask_b32_e64 v91, v94, v91, s[10:11]
	v_cndmask_b32_e64 v96, v150, v95, s[12:13]
	v_fma_f32 v90, v100, v90, v120
	v_mov_b32_dpp v150, v76 row_ror:15 row_mask:0xf bank_mask:0xf bound_ctrl:1
	v_fma_f32 v88, v108, v88, v90
	v_fma_f32 v90, v112, v91, v128
	v_mov_b32_dpp v91, v93 row_ror:1 row_mask:0xf bank_mask:0xf bound_ctrl:1
	v_fma_f32 v88, v104, v96, v88
	v_mov_b32_dpp v96, v89 row_ror:1 row_mask:0xf bank_mask:0xf bound_ctrl:1
	v_cndmask_b32_e64 v91, v96, v91, s[10:11]
	v_mov_b32_dpp v93, v97 row_ror:1 row_mask:0xf bank_mask:0xf bound_ctrl:1
	v_mov_b32_dpp v97, v87 row_ror:1 row_mask:0xf bank_mask:0xf bound_ctrl:1
	v_fma_f32 v91, v101, v91, v121
	v_cndmask_b32_e64 v144, v175, v150, s[12:13]
	v_fma_f32 v86, v116, v86, v90
	v_cndmask_b32_e64 v93, v97, v93, s[10:11]
	v_mov_b32_dpp v169, v79 row_ror:15 row_mask:0xf bank_mask:0xf bound_ctrl:1
	v_fma_f32 v89, v109, v89, v91
	v_fma_f32 v91, v113, v93, v129
; #define PG8_GAS __attribute__((address_space(1)))
; __device__ __forceinline__ unsigned cvt_pk_bf16(float lo, float hi) { const f32x2c v = {lo, hi}; return __builtin_bit_cast(unsigned, __builtin_convertvector(v, bf16x2c)); }
; __device__ __forceinline__ float fma_s(float a, float b, float c) { float d; asm("v_fma_f32 %0, %1, %2, %3" : "=v"(d) : "v"(a), "v"(b), "v"(c)); return d; }
; #define PG8_ROR1(x) dpp_ror1(x)
; #define PG8_ROR15(x) dpp_ror15(x)
;     __device__ __forceinline__ void run(f32x4 (&acc)[2][2][4][2], const Unit& un, int wr, int wc, int fr, int fq, PG8_LAS unsigned char* xl) const {
;     ...
;                 for (int m = 0; m < 4; ++m) {
;                     float o[4];
; #pragma unroll
;                     for (int e = 0; e < 4; ++e) {
;                         const float g = acc[ai][0][m][n][e], v = acc[ai][1][m][n][e];
;                         const float gpe = m > 0 ? PG8_ROR1(acc[ai][0][m - 1][n][e]) : hpg[e], vpe = m > 0 ? PG8_ROR1(acc[ai][1][m - 1][n][e]) : hpv[e];
;                         const float gne = m < 3 ? PG8_ROR15(acc[ai][0][m + 1][n][e]) : hng[e], vne = m < 3 ? PG8_ROR15(acc[ai][1][m + 1][n][e]) : hnv[e];
;                         const float gpi = PG8_ROR1(g), vpi = PG8_ROR1(v), gni = PG8_ROR15(g), vni = PG8_ROR15(v);
;                         const float gp = e0 ? gpe : gpi, vp = e0 ? vpe : vpi, gn = e15 ? gne : gni, vn = e15 ? vne : vni;
;                         const float cg = fma_s(w2g[e], gn, fma_s(w1g[e], g, fma_s(w0g[e], gp, bg[e]))), cv = fma_s(w2v[e], vn, fma_s(w1v[e], v, fma_s(w0v[e], vp, bv[e])));
;                         o[e] = (cg * cv) * __builtin_amdgcn_rcpf(1.0f + __builtin_amdgcn_exp2f(cg * -1.4426950408889634f));
;                     }
;                     if (n == 0) { keep[m].x = cvt_pk_bf16(o[0], o[1]); keep[m].y = cvt_pk_bf16(o[2], o[3]); }
;                     else { u32x4 w; w.x = keep[m].x; w.y = keep[m].y; w.z = cvt_pk_bf16(o[0], o[1]); w.w = cvt_pk_bf16(o[2], o[3]);
;                         *(PG8_GAS u32x4*)(act + (size_t)(row0 + ai * HALF + m * 16) * dff + j - 4) = w; }
	v_fma_f32 v86, v124, v144, v86
	v_mul_f32_e32 v90, 0xbfb8aa3b, v88
	v_cndmask_b32_e64 v144, v151, v169, s[12:13]
	v_fma_f32 v89, v105, v144, v89
	v_fma_f32 v87, v117, v87, v91
	v_exp_f32_e32 v90, v90
	v_mul_f32_e32 v91, 0xbfb8aa3b, v89
	v_exp_f32_e32 v91, v91
	v_mov_b32_dpp v151, v77 row_ror:15 row_mask:0xf bank_mask:0xf bound_ctrl:1
	v_add_f32_e32 v90, 1.0, v90
	v_rcp_f32_e32 v90, v90
	v_add_f32_e32 v91, 1.0, v91
	v_rcp_f32_e32 v91, v91
	v_cndmask_b32_e64 v145, v176, v151, s[12:13]
	v_fma_f32 v87, v125, v145, v87
	v_cvt_pk_bf16_f32 v144, v84, v85
	v_pk_mul_f32 v[86:87], v[88:89], v[86:87]
	v_add_u32_e32 v84, 16, v172
	v_pk_mul_f32 v[86:87], v[86:87], v[90:91]
	v_mad_i64_i32 v[84:85], s[14:15], v84, s5, v[74:75]
	v_cvt_pk_bf16_f32 v145, v86, v87
	v_lshl_add_u64 v[84:85], v[84:85], 0, v[146:147]
	v_mov_b32_dpp v86, v80 row_ror:1 row_mask:0xf bank_mask:0xf bound_ctrl:1
	global_store_dwordx4 v[84:85], v[142:145], off
	v_mov_b32_dpp v84, v66 row_ror:15 row_mask:0xf bank_mask:0xf bound_ctrl:1
	v_mov_b32_dpp v87, v82 row_ror:1 row_mask:0xf bank_mask:0xf bound_ctrl:1
	v_cndmask_b32_e64 v88, v86, v152, s[10:11]
	v_mov_b32_dpp v85, v70 row_ror:15 row_mask:0xf bank_mask:0xf bound_ctrl:1
	v_cndmask_b32_e64 v89, v87, v153, s[10:11]
	v_cndmask_b32_e64 v84, v154, v84, s[12:13]
	v_fma_f32 v88, v98, v88, v118
	v_cndmask_b32_e64 v85, v148, v85, s[12:13]
	v_fma_f32 v80, v106, v80, v88
	v_mov_b32_dpp v90, v83 row_ror:1 row_mask:0xf bank_mask:0xf bound_ctrl:1
	v_fma_f32 v80, v102, v84, v80
	v_fma_f32 v84, v110, v89, v126
	v_mov_b32_dpp v89, v81 row_ror:1 row_mask:0xf bank_mask:0xf bound_ctrl:1
	v_fma_f32 v82, v114, v82, v84
	v_cndmask_b32_e64 v91, v89, v155, s[10:11]
	v_fma_f32 v82, v122, v85, v82
	v_mov_b32_dpp v85, v67 row_ror:15 row_mask:0xf bank_mask:0xf bound_ctrl:1
	v_cndmask_b32_e64 v85, v170, v85, s[12:13]
	v_fma_f32 v91, v99, v91, v119
	v_cndmask_b32_e64 v93, v90, v168, s[10:11]
	v_fma_f32 v81, v107, v81, v91
	v_mul_f32_e32 v84, 0xbfb8aa3b, v80
	v_fma_f32 v81, v103, v85, v81
	v_fma_f32 v85, v111, v93, v127
	v_exp_f32_e32 v84, v84
	v_fma_f32 v83, v115, v83, v85
	v_mul_f32_e32 v85, 0xbfb8aa3b, v81
	v_exp_f32_e32 v85, v85
	v_add_f32_e32 v84, 1.0, v84
	v_rcp_f32_e32 v84, v84
	v_mov_b32_dpp v88, v71 row_ror:15 row_mask:0xf bank_mask:0xf bound_ctrl:1
	v_add_f32_e32 v85, 1.0, v85
	v_rcp_f32_e32 v85, v85
	v_cndmask_b32_e64 v88, v149, v88, s[12:13]
	v_fma_f32 v83, v123, v88, v83
	s_nop 0
	v_pk_mul_f32 v[80:81], v[80:81], v[82:83]
	v_mov_b32_dpp v82, v68 row_ror:15 row_mask:0xf bank_mask:0xf bound_ctrl:1
	v_pk_mul_f32 v[80:81], v[80:81], v[84:85]
	v_mov_b32_dpp v84, v78 row_ror:1 row_mask:0xf bank_mask:0xf bound_ctrl:1
	v_mov_b32_dpp v85, v76 row_ror:1 row_mask:0xf bank_mask:0xf bound_ctrl:1
	v_cndmask_b32_e64 v88, v84, v92, s[10:11]
	v_mov_b32_dpp v83, v72 row_ror:15 row_mask:0xf bank_mask:0xf bound_ctrl:1
	v_cndmask_b32_e64 v91, v85, v94, s[10:11]
	v_cndmask_b32_e64 v82, v95, v82, s[12:13]
	v_fma_f32 v88, v100, v88, v120
	v_cndmask_b32_e64 v83, v150, v83, s[12:13]
	v_fma_f32 v78, v108, v78, v88
	v_mov_b32_dpp v92, v77 row_ror:1 row_mask:0xf bank_mask:0xf bound_ctrl:1
	v_fma_f32 v78, v104, v82, v78
	v_fma_f32 v82, v112, v91, v128
	v_mov_b32_dpp v91, v79 row_ror:1 row_mask:0xf bank_mask:0xf bound_ctrl:1
	v_fma_f32 v76, v116, v76, v82
	v_cndmask_b32_e64 v93, v91, v96, s[10:11]
	v_fma_f32 v76, v124, v83, v76
	v_mov_b32_dpp v83, v69 row_ror:15 row_mask:0xf bank_mask:0xf bound_ctrl:1
	v_cndmask_b32_e64 v83, v169, v83, s[12:13]
	v_fma_f32 v93, v101, v93, v121
	v_cndmask_b32_e64 v94, v92, v97, s[10:11]
	v_fma_f32 v79, v109, v79, v93
	v_mul_f32_e32 v82, 0xbfb8aa3b, v78
	v_fma_f32 v79, v105, v83, v79
	v_fma_f32 v83, v113, v94, v129
	v_exp_f32_e32 v82, v82
	v_fma_f32 v77, v117, v77, v83
	v_mul_f32_e32 v83, 0xbfb8aa3b, v79
	v_exp_f32_e32 v83, v83
	v_add_f32_e32 v82, 1.0, v82
	v_rcp_f32_e32 v82, v82
	v_mov_b32_dpp v88, v73 row_ror:15 row_mask:0xf bank_mask:0xf bound_ctrl:1
	v_add_f32_e32 v83, 1.0, v83
	v_rcp_f32_e32 v83, v83
	v_cndmask_b32_e64 v88, v151, v88, s[12:13]
	v_fma_f32 v77, v125, v88, v77
	v_cvt_pk_bf16_f32 v142, v80, v81
	v_pk_mul_f32 v[76:77], v[78:79], v[76:77]
	v_mov_b32_dpp v78, v66 row_ror:15 row_mask:0xf bank_mask:0xf bound_ctrl:1
	v_pk_mul_f32 v[76:77], v[76:77], v[82:83]
	v_mov_b32_dpp v79, v70 row_ror:15 row_mask:0xf bank_mask:0xf bound_ctrl:1
	v_cvt_pk_bf16_f32 v143, v76, v77
; #define PG8_GAS __attribute__((address_space(1)))
;     __device__ __forceinline__ void run(f32x4 (&acc)[2][2][4][2], const Unit& un, int wr, int wc, int fr, int fq, PG8_LAS unsigned char* xl) const {
;     ...
;         for (int ai = 0; ai < 2; ++ai) { const int blk = ai * 2 + wr;
;             u32x2 keep[4];
; #pragma unroll
;             for (int n = 0; n < 2; ++n) {
;                 const int j = un.pn * 128 + cl + 4 * n;
;                 const f32x4 w0g = *(const PG8_GAS f32x4*)(cw + j), w1g = *(const PG8_GAS f32x4*)(cw + nup + j), w2g = *(const PG8_GAS f32x4*)(cw + 2 * (size_t)nup + j), bg = *(const PG8_GAS f32x4*)(cb + j);
;                 const f32x4 w0v = *(const PG8_GAS f32x4*)(cw + dff + j), w1v = *(const PG8_GAS f32x4*)(cw + nup + dff + j), w2v = *(const PG8_GAS f32x4*)(cw + 2 * (size_t)nup + dff + j), bv = *(const PG8_GAS f32x4*)(cb + dff + j);
;                 f32x4 hpg, hpv, hng, hnv;
;     ...
;                 for (int m = 0; m < 4; ++m) {
;                     float o[4];
; #pragma unroll
;                     for (int e = 0; e < 4; ++e) {
;                         const float g = acc[ai][0][m][n][e], v = acc[ai][1][m][n][e];
;                         const float gpe = m > 0 ? PG8_ROR1(acc[ai][0][m - 1][n][e]) : hpg[e], vpe = m > 0 ? PG8_ROR1(acc[ai][1][m - 1][n][e]) : hpv[e];
;                         const float gne = m < 3 ? PG8_ROR15(acc[ai][0][m + 1][n][e]) : hng[e], vne = m < 3 ? PG8_ROR15(acc[ai][1][m + 1][n][e]) : hnv[e];
;                         const float gpi = PG8_ROR1(g), vpi = PG8_ROR1(v), gni = PG8_ROR15(g), vni = PG8_ROR15(v);
;                         const float gp = e0 ? gpe : gpi, vp = e0 ? vpe : vpi, gn = e15 ? gne : gni, vn = e15 ? vne : vni;
;                         const float cg = fma_s(w2g[e], gn, fma_s(w1g[e], g, fma_s(w0g[e], gp, bg[e]))), cv = fma_s(w2v[e], vn, fma_s(w1v[e], v, fma_s(w0v[e], vp, bv[e])));
;                         o[e] = (cg * cv) * __builtin_amdgcn_rcpf(1.0f + __builtin_amdgcn_exp2f(cg * -1.4426950408889634f));
;                     }
;                     if (n == 0) { keep[m].x = cvt_pk_bf16(o[0], o[1]); keep[m].y = cvt_pk_bf16(o[2], o[3]); }
;                     else { u32x4 w; w.x = keep[m].x; w.y = keep[m].y; w.z = cvt_pk_bf16(o[0], o[1]); w.w = cvt_pk_bf16(o[2], o[3]);
;                         *(PG8_GAS u32x4*)(act + (size_t)(row0 + ai * HALF + m * 16) * dff + j - 4) = w; }
	v_add_u32_e32 v76, 32, v172
	v_mad_i64_i32 v[76:77], s[14:15], v76, s5, v[74:75]
	v_lshl_add_u64 v[76:77], v[76:77], 0, v[146:147]
	global_store_dwordx4 v[76:77], v[140:143], off
	v_cndmask_b32_e64 v78, v78, v134, s[12:13]
	v_mov_b32_dpp v76, v66 row_ror:1 row_mask:0xf bank_mask:0xf bound_ctrl:1
	v_mov_b32_dpp v77, v70 row_ror:1 row_mask:0xf bank_mask:0xf bound_ctrl:1
	v_cndmask_b32_e64 v76, v76, v86, s[10:11]
	v_cndmask_b32_e64 v77, v77, v87, s[10:11]
	v_fma_f32 v76, v98, v76, v118
	v_cndmask_b32_e64 v79, v79, v130, s[12:13]
	v_fma_f32 v66, v106, v66, v76
	v_fma_f32 v76, v110, v77, v126
	v_mov_b32_dpp v80, v71 row_ror:15 row_mask:0xf bank_mask:0xf bound_ctrl:1
	v_mov_b32_dpp v77, v67 row_ror:1 row_mask:0xf bank_mask:0xf bound_ctrl:1
	v_cndmask_b32_e64 v77, v77, v89, s[10:11]
	v_fma_f32 v66, v102, v78, v66
	v_fma_f32 v70, v114, v70, v76
	v_mov_b32_dpp v78, v71 row_ror:1 row_mask:0xf bank_mask:0xf bound_ctrl:1
	v_fma_f32 v77, v99, v77, v119
	v_fma_f32 v70, v122, v79, v70
	v_mov_b32_dpp v79, v67 row_ror:15 row_mask:0xf bank_mask:0xf bound_ctrl:1
	v_cndmask_b32_e64 v78, v78, v90, s[10:11]
	v_fma_f32 v67, v107, v67, v77
	v_fma_f32 v77, v111, v78, v127
	v_mul_f32_e32 v76, 0xbfb8aa3b, v66
	v_cndmask_b32_e64 v79, v79, v135, s[12:13]
	v_fma_f32 v67, v103, v79, v67
	v_fma_f32 v71, v115, v71, v77
	v_exp_f32_e32 v76, v76
	v_mul_f32_e32 v77, 0xbfb8aa3b, v67
	v_exp_f32_e32 v77, v77
	v_cndmask_b32_e64 v80, v80, v131, s[12:13]
	v_add_f32_e32 v76, 1.0, v76
	v_rcp_f32_e32 v76, v76
	v_add_f32_e32 v77, 1.0, v77
	v_rcp_f32_e32 v77, v77
	v_fma_f32 v71, v123, v80, v71
	v_mov_b32_dpp v78, v73 row_ror:15 row_mask:0xf bank_mask:0xf bound_ctrl:1
	v_pk_mul_f32 v[66:67], v[66:67], v[70:71]
	v_mov_b32_dpp v70, v68 row_ror:1 row_mask:0xf bank_mask:0xf bound_ctrl:1
	v_mov_b32_dpp v71, v72 row_ror:1 row_mask:0xf bank_mask:0xf bound_ctrl:1
	v_cndmask_b32_e64 v70, v70, v84, s[10:11]
	v_pk_mul_f32 v[66:67], v[66:67], v[76:77]
	v_mov_b32_dpp v76, v68 row_ror:15 row_mask:0xf bank_mask:0xf bound_ctrl:1
	v_cndmask_b32_e64 v71, v71, v85, s[10:11]
	v_fma_f32 v70, v100, v70, v120
	v_cndmask_b32_e64 v76, v76, v136, s[12:13]
	v_fma_f32 v68, v108, v68, v70
	v_fma_f32 v70, v112, v71, v128
	v_mov_b32_dpp v77, v72 row_ror:15 row_mask:0xf bank_mask:0xf bound_ctrl:1
	v_fma_f32 v68, v104, v76, v68
	v_fma_f32 v70, v116, v72, v70
	v_cndmask_b32_e64 v77, v77, v132, s[12:13]
	v_mul_f32_e32 v71, 0xbfb8aa3b, v68
	v_exp_f32_e32 v71, v71
	v_mov_b32_dpp v76, v73 row_ror:1 row_mask:0xf bank_mask:0xf bound_ctrl:1
	v_fma_f32 v70, v124, v77, v70
	v_mov_b32_dpp v77, v69 row_ror:15 row_mask:0xf bank_mask:0xf bound_ctrl:1
	v_add_f32_e32 v71, 1.0, v71
	v_rcp_f32_e32 v72, v71
	v_cndmask_b32_e64 v76, v76, v92, s[10:11]
	v_mov_b32_dpp v71, v69 row_ror:1 row_mask:0xf bank_mask:0xf bound_ctrl:1
	v_cndmask_b32_e64 v71, v71, v91, s[10:11]
	v_fma_f32 v71, v101, v71, v121
	v_cndmask_b32_e64 v77, v77, v137, s[12:13]
	v_fma_f32 v69, v109, v69, v71
	v_fma_f32 v71, v113, v76, v129
	v_cndmask_b32_e64 v78, v78, v133, s[12:13]
	v_fma_f32 v69, v105, v77, v69
	v_fma_f32 v71, v117, v73, v71
	v_cvt_pk_bf16_f32 v140, v66, v67
	v_mul_f32_e32 v73, 0xbfb8aa3b, v69
	v_exp_f32_e32 v73, v73
	v_fma_f32 v71, v125, v78, v71
	v_add_u32_e32 v66, 48, v172
	v_pk_mul_f32 v[68:69], v[68:69], v[70:71]
	v_add_f32_e32 v73, 1.0, v73
	v_rcp_f32_e32 v73, v73
	v_mad_i64_i32 v[66:67], s[14:15], v66, s5, v[74:75]
	v_lshl_add_u64 v[66:67], v[66:67], 0, v[146:147]
	v_pk_mul_f32 v[68:69], v[68:69], v[72:73]
	s_nop 0
	v_cvt_pk_bf16_f32 v141, v68, v69
	global_store_dwordx4 v[66:67], v[138:141], off
	ds_read_b128 v[86:89], v247 offset:0
	ds_read_b128 v[82:85], v247 offset:512
	ds_read_b128 v[78:81], v247 offset:1024
	ds_read_b128 v[94:97], v247 offset:3072
	ds_read_b128 v[74:77], v247 offset:1536
	ds_read_b128 v[70:73], v247 offset:2048
	ds_read_b128 v[66:69], v247 offset:2560
	ds_read_b128 v[90:93], v247 offset:3584
	v_cndmask_b32_e64 v99, 0, 1, s[44:45]
	v_add_u32_e32 v115, s92, v197
	v_add_u32_e32 v117, s93, v197
	v_mov_b32_e32 v98, 0
	v_cmp_ne_u32_e64 s[14:15], 1, v99
	s_andn2_b64 vcc, exec, s[44:45]
	v_mov_b32_e32 v106, 0
	v_mov_b32_e32 v107, 0
	v_mov_b32_e32 v108, 0
	v_mov_b32_e32 v109, 0
	v_mov_b32_e32 v110, 0
	v_mov_b32_e32 v111, 0
	v_mov_b32_e32 v112, 0
	v_mov_b32_e32 v113, 0
	s_cbranch_vccnz .LBB0_804
	ds_read_b128 v[110:113], v117
	ds_read_b128 v[106:109], v115

; __device__ __forceinline__ float fma_s(float a, float b, float c) { float d; asm("v_fma_f32 %0, %1, %2, %3" : "=v"(d) : "v"(a), "v"(b), "v"(c)); return d; }
; #define PG8_ROR1(x) dpp_ror1(x)
; #define PG8_ROR15(x) dpp_ror15(x)
;     __device__ __forceinline__ void run(f32x4 (&acc)[2][2][4][2], const Unit& un, int wr, int wc, int fr, int fq, PG8_LAS unsigned char* xl) const {
;     ...
;             for (int m = 0; m < 4; ++m) { const float iv = __builtin_amdgcn_rsqf(ssq[(size_t)un.pm * BM + wr * 64 + fr + ai * HALF + m * 16] * inv_n + eps);
; #pragma unroll
;                 for (int bj = 0; bj < 2; ++bj)
; #pragma unroll
;                     for (int n = 0; n < 2; ++n) acc[ai][bj][m][n] = acc[ai][bj][m][n] * iv; }
;     ...
;                     for (int e = 0; e < 4; ++e) {
;                         const float g = acc[ai][0][m][n][e], v = acc[ai][1][m][n][e];
;                         const float gpe = m > 0 ? PG8_ROR1(acc[ai][0][m - 1][n][e]) : hpg[e], vpe = m > 0 ? PG8_ROR1(acc[ai][1][m - 1][n][e]) : hpv[e];
;                         const float gne = m < 3 ? PG8_ROR15(acc[ai][0][m + 1][n][e]) : hng[e], vne = m < 3 ? PG8_ROR15(acc[ai][1][m + 1][n][e]) : hnv[e];
;                         const float gpi = PG8_ROR1(g), vpi = PG8_ROR1(v), gni = PG8_ROR15(g), vni = PG8_ROR15(v);
;                         const float gp = e0 ? gpe : gpi, vp = e0 ? vpe : vpi, gn = e15 ? gne : gni, vn = e15 ? vne : vni;
;                         const float cg = fma_s(w2g[e], gn, fma_s(w1g[e], g, fma_s(w0g[e], gp, bg[e]))), cv = fma_s(w2v[e], vn, fma_s(w1v[e], v, fma_s(w0v[e], vp, bv[e])));
.LBB0_806:
	v_fmamk_f32 v114, v245, 0x39800000, v244
	v_fmamk_f32 v116, v211, 0x39800000, v244
	v_rsq_f32_e32 v114, v114
	v_rsq_f32_e32 v116, v116
	v_pk_mul_f32 v[124:125], v[32:33], v[114:115] op_sel_hi:[1,0]
	v_pk_mul_f32 v[32:33], v[34:35], v[116:117] op_sel_hi:[1,0]
	v_mov_b32_dpp v34, v58 row_ror:1 row_mask:0xf bank_mask:0xf bound_ctrl:1
	s_waitcnt lgkmcnt(1)
	v_cndmask_b32_e64 v34, v34, v110, s[10:11]
	v_pk_mul_f32 v[42:43], v[42:43], v[114:115] op_sel_hi:[1,0]
	s_waitcnt lgkmcnt(0)
	v_fma_f32 v34, v86, v34, v94
	v_pk_mul_f32 v[120:121], v[30:31], v[114:115] op_sel_hi:[1,0]
	v_pk_mul_f32 v[30:31], v[36:37], v[116:117] op_sel_hi:[1,0]
	v_mov_b32_dpp v35, v62 row_ror:1 row_mask:0xf bank_mask:0xf bound_ctrl:1
	v_mov_b32_dpp v36, v58 row_ror:15 row_mask:0xf bank_mask:0xf bound_ctrl:1
	v_mov_b32_dpp v118, v42 row_ror:15 row_mask:0xf bank_mask:0xf bound_ctrl:1
	v_fma_f32 v34, v82, v58, v34
	s_waitcnt lgkmcnt(0)
	v_cndmask_b32_e64 v35, v35, v106, s[10:11]
	v_cndmask_b32_e64 v36, v36, v118, s[12:13]
	v_fma_f32 v106, v78, v36, v34
	s_waitcnt lgkmcnt(0)
	v_fma_f32 v34, v74, v35, v90
	v_mov_b32_dpp v37, v62 row_ror:15 row_mask:0xf bank_mask:0xf bound_ctrl:1
	v_mov_b32_dpp v119, v120 row_ror:15 row_mask:0xf bank_mask:0xf bound_ctrl:1
	v_fma_f32 v34, v70, v62, v34
	v_cndmask_b32_e64 v37, v37, v119, s[12:13]
	v_fma_f32 v110, v66, v37, v34
	v_mov_b32_dpp v35, v63 row_ror:1 row_mask:0xf bank_mask:0xf bound_ctrl:1
	v_mov_b32_dpp v34, v59 row_ror:1 row_mask:0xf bank_mask:0xf bound_ctrl:1
	v_cndmask_b32_e64 v34, v34, v111, s[10:11]
	v_fma_f32 v34, v87, v34, v95
	v_mov_b32_dpp v36, v59 row_ror:15 row_mask:0xf bank_mask:0xf bound_ctrl:1
	v_mov_b32_dpp v122, v43 row_ror:15 row_mask:0xf bank_mask:0xf bound_ctrl:1
	v_fma_f32 v34, v83, v59, v34
	v_cndmask_b32_e64 v35, v35, v107, s[10:11]
	v_cndmask_b32_e64 v36, v36, v122, s[12:13]
	v_fma_f32 v107, v79, v36, v34
	v_fma_f32 v34, v75, v35, v91
	v_mov_b32_dpp v37, v63 row_ror:15 row_mask:0xf bank_mask:0xf bound_ctrl:1
	v_mov_b32_dpp v123, v121 row_ror:15 row_mask:0xf bank_mask:0xf bound_ctrl:1
	v_fma_f32 v34, v71, v63, v34
	v_cndmask_b32_e64 v37, v37, v123, s[12:13]
	v_fma_f32 v111, v67, v37, v34
	v_pk_mul_f32 v[44:45], v[44:45], v[114:115] op_sel_hi:[1,0]
	v_mov_b32_dpp v34, v60 row_ror:1 row_mask:0xf bank_mask:0xf bound_ctrl:1
	v_cndmask_b32_e64 v34, v34, v112, s[10:11]
	v_fma_f32 v34, v88, v34, v96
	v_mov_b32_dpp v35, v64 row_ror:1 row_mask:0xf bank_mask:0xf bound_ctrl:1
	v_mov_b32_dpp v36, v60 row_ror:15 row_mask:0xf bank_mask:0xf bound_ctrl:1
	v_mov_b32_dpp v126, v44 row_ror:15 row_mask:0xf bank_mask:0xf bound_ctrl:1
	v_fma_f32 v34, v84, v60, v34
	v_cndmask_b32_e64 v35, v35, v108, s[10:11]
	v_cndmask_b32_e64 v36, v36, v126, s[12:13]
	v_fma_f32 v108, v80, v36, v34
	v_fma_f32 v34, v76, v35, v92
	v_mov_b32_dpp v37, v64 row_ror:15 row_mask:0xf bank_mask:0xf bound_ctrl:1
	v_mov_b32_dpp v127, v124 row_ror:15 row_mask:0xf bank_mask:0xf bound_ctrl:1
	v_fma_f32 v34, v72, v64, v34
	v_cndmask_b32_e64 v37, v37, v127, s[12:13]
	v_fma_f32 v112, v68, v37, v34
	v_mov_b32_dpp v35, v65 row_ror:1 row_mask:0xf bank_mask:0xf bound_ctrl:1
	v_mov_b32_dpp v34, v61 row_ror:1 row_mask:0xf bank_mask:0xf bound_ctrl:1
	v_cndmask_b32_e64 v34, v34, v113, s[10:11]
	v_fma_f32 v34, v89, v34, v97
	v_mov_b32_dpp v36, v61 row_ror:15 row_mask:0xf bank_mask:0xf bound_ctrl:1
	v_mov_b32_dpp v128, v45 row_ror:15 row_mask:0xf bank_mask:0xf bound_ctrl:1
	v_fma_f32 v34, v85, v61, v34
	v_cndmask_b32_e64 v35, v35, v109, s[10:11]
	v_cndmask_b32_e64 v36, v36, v128, s[12:13]
	v_fma_f32 v109, v81, v36, v34
	v_fma_f32 v34, v77, v35, v93
	v_mov_b32_dpp v37, v65 row_ror:15 row_mask:0xf bank_mask:0xf bound_ctrl:1
	v_mov_b32_dpp v129, v125 row_ror:15 row_mask:0xf bank_mask:0xf bound_ctrl:1
	v_fma_f32 v34, v73, v65, v34
	v_cndmask_b32_e64 v37, v37, v129, s[12:13]
	v_fma_f32 v113, v69, v37, v34
	v_mov_b32_dpp v36, v42 row_ror:1 row_mask:0xf bank_mask:0xf bound_ctrl:1
	v_mov_b32_dpp v34, v58 row_ror:1 row_mask:0xf bank_mask:0xf bound_ctrl:1
	v_cndmask_b32_e64 v34, v36, v34, s[10:11]
	v_fma_f32 v34, v86, v34, v94
	v_mov_b32_dpp v35, v62 row_ror:1 row_mask:0xf bank_mask:0xf bound_ctrl:1
	v_mov_b32_dpp v37, v120 row_ror:1 row_mask:0xf bank_mask:0xf bound_ctrl:1
	v_mov_b32_dpp v58, v32 row_ror:15 row_mask:0xf bank_mask:0xf bound_ctrl:1
	v_fma_f32 v34, v82, v42, v34
	v_pk_mul_f32 v[26:27], v[26:27], v[116:117] op_sel_hi:[1,0]
	v_cndmask_b32_e64 v35, v37, v35, s[10:11]
	v_cndmask_b32_e64 v62, v118, v58, s[12:13]
	v_fma_f32 v118, v78, v62, v34
	v_fma_f32 v34, v74, v35, v90
	v_mov_b32_dpp v130, v26 row_ror:15 row_mask:0xf bank_mask:0xf bound_ctrl:1
	v_fma_f32 v34, v70, v120, v34
	v_cndmask_b32_e64 v119, v119, v130, s[12:13]
	v_fma_f32 v120, v66, v119, v34
	v_mov_b32_dpp v42, v43 row_ror:1 row_mask:0xf bank_mask:0xf bound_ctrl:1
	v_mov_b32_dpp v34, v59 row_ror:1 row_mask:0xf bank_mask:0xf bound_ctrl:1
	v_cndmask_b32_e64 v34, v42, v34, s[10:11]
	v_fma_f32 v34, v87, v34, v95
	v_mov_b32_dpp v35, v63 row_ror:1 row_mask:0xf bank_mask:0xf bound_ctrl:1
	v_mov_b32_dpp v59, v121 row_ror:1 row_mask:0xf bank_mask:0xf bound_ctrl:1
	v_mov_b32_dpp v62, v33 row_ror:15 row_mask:0xf bank_mask:0xf bound_ctrl:1
	v_fma_f32 v34, v83, v43, v34
	v_cndmask_b32_e64 v35, v59, v35, s[10:11]
	v_cndmask_b32_e64 v63, v122, v62, s[12:13]
	v_fma_f32 v119, v79, v63, v34
	v_fma_f32 v34, v75, v35, v91
	v_mov_b32_dpp v131, v27 row_ror:15 row_mask:0xf bank_mask:0xf bound_ctrl:1
	v_fma_f32 v34, v71, v121, v34
	v_cndmask_b32_e64 v122, v123, v131, s[12:13]
	v_fma_f32 v121, v67, v122, v34
	v_mov_b32_dpp v43, v44 row_ror:1 row_mask:0xf bank_mask:0xf bound_ctrl:1
	v_mov_b32_dpp v34, v60 row_ror:1 row_mask:0xf bank_mask:0xf bound_ctrl:1
; __device__ __forceinline__ float fma_s(float a, float b, float c) { float d; asm("v_fma_f32 %0, %1, %2, %3" : "=v"(d) : "v"(a), "v"(b), "v"(c)); return d; }
; #define PG8_ROR1(x) dpp_ror1(x)
; #define PG8_ROR15(x) dpp_ror15(x)
;     __device__ __forceinline__ void run(f32x4 (&acc)[2][2][4][2], const Unit& un, int wr, int wc, int fr, int fq, PG8_LAS unsigned char* xl) const {
;     ...
;                     for (int e = 0; e < 4; ++e) {
;                         const float g = acc[ai][0][m][n][e], v = acc[ai][1][m][n][e];
;                         const float gpe = m > 0 ? PG8_ROR1(acc[ai][0][m - 1][n][e]) : hpg[e], vpe = m > 0 ? PG8_ROR1(acc[ai][1][m - 1][n][e]) : hpv[e];
;                         const float gne = m < 3 ? PG8_ROR15(acc[ai][0][m + 1][n][e]) : hng[e], vne = m < 3 ? PG8_ROR15(acc[ai][1][m + 1][n][e]) : hnv[e];
;                         const float gpi = PG8_ROR1(g), vpi = PG8_ROR1(v), gni = PG8_ROR15(g), vni = PG8_ROR15(v);
;                         const float gp = e0 ? gpe : gpi, vp = e0 ? vpe : vpi, gn = e15 ? gne : gni, vn = e15 ? vne : vni;
;                         const float cg = fma_s(w2g[e], gn, fma_s(w1g[e], g, fma_s(w0g[e], gp, bg[e]))), cv = fma_s(w2v[e], vn, fma_s(w1v[e], v, fma_s(w0v[e], vp, bv[e])));
	v_cndmask_b32_e64 v34, v43, v34, s[10:11]
	v_fma_f32 v34, v88, v34, v96
	v_mov_b32_dpp v35, v64 row_ror:1 row_mask:0xf bank_mask:0xf bound_ctrl:1
	v_mov_b32_dpp v60, v124 row_ror:1 row_mask:0xf bank_mask:0xf bound_ctrl:1
	v_mov_b32_dpp v63, v30 row_ror:15 row_mask:0xf bank_mask:0xf bound_ctrl:1
	v_fma_f32 v34, v84, v44, v34
	v_pk_mul_f32 v[28:29], v[28:29], v[116:117] op_sel_hi:[1,0]
	v_cndmask_b32_e64 v35, v60, v35, s[10:11]
	v_cndmask_b32_e64 v64, v126, v63, s[12:13]
	v_fma_f32 v122, v80, v64, v34
	v_fma_f32 v34, v76, v35, v92
	v_mov_b32_dpp v132, v28 row_ror:15 row_mask:0xf bank_mask:0xf bound_ctrl:1
	v_fma_f32 v34, v72, v124, v34
	v_cndmask_b32_e64 v123, v127, v132, s[12:13]
	v_fma_f32 v124, v68, v123, v34
	v_mov_b32_dpp v44, v45 row_ror:1 row_mask:0xf bank_mask:0xf bound_ctrl:1
	v_mov_b32_dpp v34, v61 row_ror:1 row_mask:0xf bank_mask:0xf bound_ctrl:1
	v_cndmask_b32_e64 v34, v44, v34, s[10:11]
	v_fma_f32 v34, v89, v34, v97
	v_mov_b32_dpp v35, v65 row_ror:1 row_mask:0xf bank_mask:0xf bound_ctrl:1
	v_mov_b32_dpp v61, v125 row_ror:1 row_mask:0xf bank_mask:0xf bound_ctrl:1
	v_mov_b32_dpp v64, v31 row_ror:15 row_mask:0xf bank_mask:0xf bound_ctrl:1
	v_fma_f32 v34, v85, v45, v34
	v_cndmask_b32_e64 v35, v61, v35, s[10:11]
	v_cndmask_b32_e64 v65, v128, v64, s[12:13]
	v_fma_f32 v123, v81, v65, v34
	v_fma_f32 v34, v77, v35, v93
	v_mov_b32_dpp v45, v32 row_ror:1 row_mask:0xf bank_mask:0xf bound_ctrl:1
	v_mov_b32_dpp v133, v29 row_ror:15 row_mask:0xf bank_mask:0xf bound_ctrl:1
	v_fma_f32 v34, v73, v125, v34
	v_cndmask_b32_e64 v36, v45, v36, s[10:11]
	v_cndmask_b32_e64 v126, v129, v133, s[12:13]
	v_fma_f32 v125, v69, v126, v34
	v_mov_b32_dpp v34, v50 row_ror:15 row_mask:0xf bank_mask:0xf bound_ctrl:1
	v_mov_b32_dpp v65, v26 row_ror:1 row_mask:0xf bank_mask:0xf bound_ctrl:1
	v_fma_f32 v36, v86, v36, v94
	v_mov_b32_dpp v35, v54 row_ror:15 row_mask:0xf bank_mask:0xf bound_ctrl:1
	v_fma_f32 v32, v82, v32, v36
	v_cndmask_b32_e64 v37, v65, v37, s[10:11]
	v_cndmask_b32_e64 v34, v58, v34, s[12:13]
	v_fma_f32 v126, v78, v34, v32
	v_fma_f32 v32, v74, v37, v90
	v_cndmask_b32_e64 v35, v130, v35, s[12:13]
	v_fma_f32 v26, v70, v26, v32
	s_nop 0
	v_fma_f32 v128, v66, v35, v26
	v_mov_b32_dpp v34, v33 row_ror:1 row_mask:0xf bank_mask:0xf bound_ctrl:1
	v_mov_b32_dpp v26, v51 row_ror:15 row_mask:0xf bank_mask:0xf bound_ctrl:1
	v_mov_b32_dpp v35, v27 row_ror:1 row_mask:0xf bank_mask:0xf bound_ctrl:1
	v_cndmask_b32_e64 v36, v34, v42, s[10:11]
	v_cndmask_b32_e64 v26, v62, v26, s[12:13]
	v_mov_b32_dpp v32, v55 row_ror:15 row_mask:0xf bank_mask:0xf bound_ctrl:1
	v_cndmask_b32_e64 v37, v35, v59, s[10:11]
	v_fma_f32 v36, v87, v36, v95
	v_cndmask_b32_e64 v32, v131, v32, s[12:13]
	v_fma_f32 v33, v83, v33, v36
	s_nop 0
	v_fma_f32 v127, v79, v26, v33
	v_fma_f32 v26, v75, v37, v91
	s_nop 0
	v_fma_f32 v26, v71, v27, v26
	v_mov_b32_dpp v33, v28 row_ror:1 row_mask:0xf bank_mask:0xf bound_ctrl:1
	v_fma_f32 v129, v67, v32, v26
	v_mov_b32_dpp v32, v30 row_ror:1 row_mask:0xf bank_mask:0xf bound_ctrl:1
	v_mov_b32_dpp v26, v52 row_ror:15 row_mask:0xf bank_mask:0xf bound_ctrl:1
	v_cndmask_b32_e64 v36, v32, v43, s[10:11]
	v_cndmask_b32_e64 v26, v63, v26, s[12:13]
	v_cndmask_b32_e64 v37, v33, v60, s[10:11]
	v_fma_f32 v36, v88, v36, v96
	v_mov_b32_dpp v27, v56 row_ror:15 row_mask:0xf bank_mask:0xf bound_ctrl:1
	v_fma_f32 v30, v84, v30, v36
	v_cndmask_b32_e64 v27, v132, v27, s[12:13]
	v_fma_f32 v130, v80, v26, v30
	v_fma_f32 v26, v76, v37, v92
	s_nop 0
	v_fma_f32 v26, v72, v28, v26
	v_mov_b32_dpp v28, v31 row_ror:1 row_mask:0xf bank_mask:0xf bound_ctrl:1
	v_fma_f32 v132, v68, v27, v26
	v_mov_b32_dpp v30, v29 row_ror:1 row_mask:0xf bank_mask:0xf bound_ctrl:1
	v_mov_b32_dpp v26, v53 row_ror:15 row_mask:0xf bank_mask:0xf bound_ctrl:1
; #define PG8_LAS __attribute__((address_space(3)))
; #define PG8_GAS __attribute__((address_space(1)))
; __device__ __forceinline__ float fma_s(float a, float b, float c) { float d; asm("v_fma_f32 %0, %1, %2, %3" : "=v"(d) : "v"(a), "v"(b), "v"(c)); return d; }
; #define PG8_ROR1(x) dpp_ror1(x)
; #define PG8_ROR15(x) dpp_ror15(x)
;     __device__ __forceinline__ void run(f32x4 (&acc)[2][2][4][2], const Unit& un, int wr, int wc, int fr, int fq, PG8_LAS unsigned char* xl) const {
;     ...
;                 const int j = un.pn * 128 + cl + 4 * n;
;                 const f32x4 w0g = *(const PG8_GAS f32x4*)(cw + j), w1g = *(const PG8_GAS f32x4*)(cw + nup + j), w2g = *(const PG8_GAS f32x4*)(cw + 2 * (size_t)nup + j), bg = *(const PG8_GAS f32x4*)(cb + j);
;                 const f32x4 w0v = *(const PG8_GAS f32x4*)(cw + dff + j), w1v = *(const PG8_GAS f32x4*)(cw + nup + dff + j), w2v = *(const PG8_GAS f32x4*)(cw + 2 * (size_t)nup + dff + j), bv = *(const PG8_GAS f32x4*)(cb + dff + j);
;                 f32x4 hpg, hpv, hng, hnv;
;                 if (blk > 0) { hpg = *(const PG8_LAS f32x4*)(X + ((blk - 1) * 2 + 1) * 256 + cl + 4 * n); hpv = *(const PG8_LAS f32x4*)(X + ((blk - 1) * 2 + 1) * 256 + 128 + cl + 4 * n); } else { hpg = (f32x4){0.f, 0.f, 0.f, 0.f}; hpv = hpg; }
;                 if (blk < 3) { hng = *(const PG8_LAS f32x4*)(X + ((blk + 1) * 2 + 0) * 256 + cl + 4 * n); hnv = *(const PG8_LAS f32x4*)(X + ((blk + 1) * 2 + 0) * 256 + 128 + cl + 4 * n); } else { hng = (f32x4){0.f, 0.f, 0.f, 0.f}; hnv = hng; }
;     ...
;                     for (int e = 0; e < 4; ++e) {
;                         const float g = acc[ai][0][m][n][e], v = acc[ai][1][m][n][e];
;                         const float gpe = m > 0 ? PG8_ROR1(acc[ai][0][m - 1][n][e]) : hpg[e], vpe = m > 0 ? PG8_ROR1(acc[ai][1][m - 1][n][e]) : hpv[e];
;                         const float gne = m < 3 ? PG8_ROR15(acc[ai][0][m + 1][n][e]) : hng[e], vne = m < 3 ? PG8_ROR15(acc[ai][1][m + 1][n][e]) : hnv[e];
;                         const float gpi = PG8_ROR1(g), vpi = PG8_ROR1(v), gni = PG8_ROR15(g), vni = PG8_ROR15(v);
;                         const float gp = e0 ? gpe : gpi, vp = e0 ? vpe : vpi, gn = e15 ? gne : gni, vn = e15 ? vne : vni;
;                         const float cg = fma_s(w2g[e], gn, fma_s(w1g[e], g, fma_s(w0g[e], gp, bg[e]))), cv = fma_s(w2v[e], vn, fma_s(w1v[e], v, fma_s(w0v[e], vp, bv[e])));
	v_cndmask_b32_e64 v36, v28, v44, s[10:11]
	v_cndmask_b32_e64 v26, v64, v26, s[12:13]
	v_cndmask_b32_e64 v37, v30, v61, s[10:11]
	v_fma_f32 v36, v89, v36, v97
	v_mov_b32_dpp v27, v57 row_ror:15 row_mask:0xf bank_mask:0xf bound_ctrl:1
	v_fma_f32 v31, v85, v31, v36
	v_cndmask_b32_e64 v27, v133, v27, s[12:13]
	v_fma_f32 v131, v81, v26, v31
	v_fma_f32 v26, v77, v37, v93
	s_nop 0
	v_fma_f32 v26, v73, v29, v26
	v_mov_b32_dpp v29, v50 row_ror:15 row_mask:0xf bank_mask:0xf bound_ctrl:1
	v_fma_f32 v133, v69, v27, v26
	v_mov_b32_dpp v27, v54 row_ror:1 row_mask:0xf bank_mask:0xf bound_ctrl:1
	v_mov_b32_dpp v26, v50 row_ror:1 row_mask:0xf bank_mask:0xf bound_ctrl:1
	v_cndmask_b32_e64 v26, v26, v45, s[10:11]
	v_fma_f32 v26, v86, v26, v94
	v_cndmask_b32_e64 v27, v27, v65, s[10:11]
	v_fma_f32 v26, v82, v50, v26
	v_cndmask_b32_e64 v29, v29, v102, s[12:13]
	v_fma_f32 v94, v78, v29, v26
	v_fma_f32 v26, v74, v27, v90
	v_mov_b32_dpp v31, v54 row_ror:15 row_mask:0xf bank_mask:0xf bound_ctrl:1
	v_fma_f32 v26, v70, v54, v26
	v_cndmask_b32_e64 v31, v31, v98, s[12:13]
	v_fma_f32 v90, v66, v31, v26
	v_mov_b32_dpp v27, v55 row_ror:1 row_mask:0xf bank_mask:0xf bound_ctrl:1
	v_mov_b32_dpp v26, v51 row_ror:1 row_mask:0xf bank_mask:0xf bound_ctrl:1
	v_cndmask_b32_e64 v26, v26, v34, s[10:11]
	v_fma_f32 v26, v87, v26, v95
	v_mov_b32_dpp v29, v51 row_ror:15 row_mask:0xf bank_mask:0xf bound_ctrl:1
	v_fma_f32 v26, v83, v51, v26
	v_cndmask_b32_e64 v27, v27, v35, s[10:11]
	v_cndmask_b32_e64 v29, v29, v103, s[12:13]
	v_fma_f32 v95, v79, v29, v26
	v_fma_f32 v26, v75, v27, v91
	v_mov_b32_dpp v31, v55 row_ror:15 row_mask:0xf bank_mask:0xf bound_ctrl:1
	v_fma_f32 v26, v71, v55, v26
	v_cndmask_b32_e64 v31, v31, v99, s[12:13]
	v_fma_f32 v91, v67, v31, v26
	v_mov_b32_dpp v27, v56 row_ror:1 row_mask:0xf bank_mask:0xf bound_ctrl:1
	v_mov_b32_dpp v26, v52 row_ror:1 row_mask:0xf bank_mask:0xf bound_ctrl:1
	v_cndmask_b32_e64 v26, v26, v32, s[10:11]
	v_fma_f32 v26, v88, v26, v96
	v_mov_b32_dpp v29, v52 row_ror:15 row_mask:0xf bank_mask:0xf bound_ctrl:1
	v_fma_f32 v26, v84, v52, v26
	v_cndmask_b32_e64 v27, v27, v33, s[10:11]
	v_cndmask_b32_e64 v29, v29, v104, s[12:13]
	v_fma_f32 v88, v80, v29, v26
	v_fma_f32 v26, v76, v27, v92
	v_mov_b32_dpp v31, v56 row_ror:15 row_mask:0xf bank_mask:0xf bound_ctrl:1
	v_fma_f32 v26, v72, v56, v26
	v_cndmask_b32_e64 v31, v31, v100, s[12:13]
	v_fma_f32 v92, v68, v31, v26
	v_mov_b32_dpp v27, v57 row_ror:1 row_mask:0xf bank_mask:0xf bound_ctrl:1
	v_mov_b32_dpp v26, v53 row_ror:1 row_mask:0xf bank_mask:0xf bound_ctrl:1
	v_cndmask_b32_e64 v26, v26, v28, s[10:11]
	v_fma_f32 v26, v89, v26, v97
	v_mov_b32_dpp v29, v53 row_ror:15 row_mask:0xf bank_mask:0xf bound_ctrl:1
	v_mov_b32_dpp v31, v57 row_ror:15 row_mask:0xf bank_mask:0xf bound_ctrl:1
	v_fma_f32 v26, v85, v53, v26
	v_cndmask_b32_e64 v27, v27, v30, s[10:11]
	v_cndmask_b32_e64 v28, v29, v105, s[12:13]
	v_cndmask_b32_e64 v29, v31, v101, s[12:13]
	v_fma_f32 v89, v81, v28, v26
	v_fma_f32 v26, v77, v27, v93
	s_nop 0
	v_fma_f32 v26, v73, v57, v26
	s_nop 0
	v_fma_f32 v93, v69, v29, v26
	ds_read_b128 v[62:65], v247 offset:16
	ds_read_b128 v[58:61], v247 offset:528
	ds_read_b128 v[54:57], v247 offset:1040
	ds_read_b128 v[66:69], v247 offset:3088
	ds_read_b128 v[34:37], v247 offset:1552
	ds_read_b128 v[26:29], v247 offset:2064
	ds_read_b128 v[30:33], v247 offset:2576
	ds_read_b128 v[42:45], v247 offset:3600
	v_mov_b32_e32 v50, 0
	s_and_b64 vcc, exec, s[14:15]
	v_mov_b32_e32 v74, 0
	v_mov_b32_e32 v75, 0
	v_mov_b32_e32 v76, 0
	v_mov_b32_e32 v77, 0
	v_mov_b32_e32 v78, 0
	v_mov_b32_e32 v79, 0
	v_mov_b32_e32 v80, 0
	v_mov_b32_e32 v81, 0
	s_cbranch_vccnz .LBB0_808
	ds_read_b128 v[78:81], v117 offset:16
	ds_read_b128 v[74:77], v115 offset:16

; #define PG8_GAS __attribute__((address_space(1)))
; __device__ __forceinline__ unsigned cvt_pk_bf16(float lo, float hi) { const f32x2c v = {lo, hi}; return __builtin_bit_cast(unsigned, __builtin_convertvector(v, bf16x2c)); }
; __device__ __forceinline__ float fma_s(float a, float b, float c) { float d; asm("v_fma_f32 %0, %1, %2, %3" : "=v"(d) : "v"(a), "v"(b), "v"(c)); return d; }
; #define PG8_ROR1(x) dpp_ror1(x)
; #define PG8_ROR15(x) dpp_ror15(x)
;     __device__ __forceinline__ void run(f32x4 (&acc)[2][2][4][2], const Unit& un, int wr, int wc, int fr, int fq, PG8_LAS unsigned char* xl) const {
;     ...
;                 for (int m = 0; m < 4; ++m) {
;                     float o[4];
; #pragma unroll
;                     for (int e = 0; e < 4; ++e) {
;                         const float g = acc[ai][0][m][n][e], v = acc[ai][1][m][n][e];
;                         const float gpe = m > 0 ? PG8_ROR1(acc[ai][0][m - 1][n][e]) : hpg[e], vpe = m > 0 ? PG8_ROR1(acc[ai][1][m - 1][n][e]) : hpv[e];
;                         const float gne = m < 3 ? PG8_ROR15(acc[ai][0][m + 1][n][e]) : hng[e], vne = m < 3 ? PG8_ROR15(acc[ai][1][m + 1][n][e]) : hnv[e];
;                         const float gpi = PG8_ROR1(g), vpi = PG8_ROR1(v), gni = PG8_ROR15(g), vni = PG8_ROR15(v);
;                         const float gp = e0 ? gpe : gpi, vp = e0 ? vpe : vpi, gn = e15 ? gne : gni, vn = e15 ? vne : vni;
;                         const float cg = fma_s(w2g[e], gn, fma_s(w1g[e], g, fma_s(w0g[e], gp, bg[e]))), cv = fma_s(w2v[e], vn, fma_s(w1v[e], v, fma_s(w0v[e], vp, bv[e])));
;                         o[e] = (cg * cv) * __builtin_amdgcn_rcpf(1.0f + __builtin_amdgcn_exp2f(cg * -1.4426950408889634f));
;                     }
;                     if (n == 0) { keep[m].x = cvt_pk_bf16(o[0], o[1]); keep[m].y = cvt_pk_bf16(o[2], o[3]); }
;                     else { u32x4 w; w.x = keep[m].x; w.y = keep[m].y; w.z = cvt_pk_bf16(o[0], o[1]); w.w = cvt_pk_bf16(o[2], o[3]);
;                         *(PG8_GAS u32x4*)(act + (size_t)(row0 + ai * HALF + m * 16) * dff + j - 4) = w; }
.LBB0_810:
	v_mov_b32_e32 v115, v114
	v_mov_b32_e32 v117, v116
	v_mov_b32_e32 v84, v114
	v_mov_b32_e32 v85, v114
	v_pk_mul_f32 v[82:83], v[16:17], v[84:85]
	v_pk_mul_f32 v[86:87], v[14:15], v[114:115]
	v_pk_mul_f32 v[8:9], v[8:9], v[84:85]
	v_pk_mul_f32 v[84:85], v[6:7], v[114:115]
	v_mov_b32_e32 v6, v116
	v_mov_b32_e32 v7, v116
	v_pk_mul_f32 v[14:15], v[2:3], v[116:117]
	v_mul_f32_e32 v2, 0xbfb8aa3b, v88
	v_pk_mul_f32 v[16:17], v[10:11], v[116:117]
	v_pk_mul_f32 v[10:11], v[4:5], v[6:7]
	v_exp_f32_e32 v4, v2
	v_mul_f32_e32 v2, 0xbfb8aa3b, v89
	v_pk_mul_f32 v[12:13], v[12:13], v[6:7]
	v_exp_f32_e32 v5, v2
	v_mul_f32_e32 v6, 0xbfb8aa3b, v94
	v_mul_f32_e32 v7, 0xbfb8aa3b, v95
	v_exp_f32_e32 v6, v6
	v_exp_f32_e32 v7, v7
	v_add_f32_e32 v4, 1.0, v4
	v_add_f32_e32 v5, 1.0, v5
	v_rcp_f32_e32 v4, v4
	v_rcp_f32_e32 v5, v5
	v_add_f32_e32 v6, 1.0, v6
	v_add_f32_e32 v7, 1.0, v7
	v_rcp_f32_e32 v6, v6
	v_rcp_f32_e32 v7, v7
	v_pk_mul_f32 v[2:3], v[88:89], v[92:93]
	v_mul_f32_e32 v88, 0xbfb8aa3b, v126
	v_pk_mul_f32 v[2:3], v[2:3], v[4:5]
	v_pk_mul_f32 v[4:5], v[94:95], v[90:91]
	v_cvt_pk_bf16_f32 v3, v2, v3
	v_pk_mul_f32 v[4:5], v[4:5], v[6:7]
	v_mul_f32_e32 v89, 0xbfb8aa3b, v127
	v_cvt_pk_bf16_f32 v2, v4, v5
	v_mul_f32_e32 v4, 0xbfb8aa3b, v130
	v_exp_f32_e32 v6, v4
	v_mul_f32_e32 v4, 0xbfb8aa3b, v131
	v_exp_f32_e32 v7, v4
	v_exp_f32_e32 v88, v88
	v_exp_f32_e32 v89, v89
	v_add_f32_e32 v6, 1.0, v6
	v_add_f32_e32 v7, 1.0, v7
	v_rcp_f32_e32 v6, v6
	v_rcp_f32_e32 v7, v7
	v_add_f32_e32 v88, 1.0, v88
	v_add_f32_e32 v89, 1.0, v89
	v_rcp_f32_e32 v88, v88
	v_rcp_f32_e32 v89, v89
	v_pk_mul_f32 v[4:5], v[130:131], v[132:133]
	v_mul_f32_e32 v90, 0xbfb8aa3b, v118
	v_pk_mul_f32 v[4:5], v[4:5], v[6:7]
	v_pk_mul_f32 v[6:7], v[126:127], v[128:129]
	v_cvt_pk_bf16_f32 v5, v4, v5
	v_pk_mul_f32 v[6:7], v[6:7], v[88:89]
	v_mul_f32_e32 v91, 0xbfb8aa3b, v119
	v_cvt_pk_bf16_f32 v4, v6, v7
	v_mul_f32_e32 v6, 0xbfb8aa3b, v122
	v_exp_f32_e32 v88, v6
	v_mul_f32_e32 v6, 0xbfb8aa3b, v123
	v_exp_f32_e32 v89, v6
	v_exp_f32_e32 v90, v90
	v_exp_f32_e32 v91, v91
	v_add_f32_e32 v88, 1.0, v88
	v_add_f32_e32 v89, 1.0, v89
	v_rcp_f32_e32 v88, v88
	v_rcp_f32_e32 v89, v89
	v_add_f32_e32 v90, 1.0, v90
	v_add_f32_e32 v91, 1.0, v91
	v_rcp_f32_e32 v90, v90
	v_rcp_f32_e32 v91, v91
	v_pk_mul_f32 v[6:7], v[122:123], v[124:125]
	v_mul_f32_e32 v92, 0xbfb8aa3b, v106
	v_pk_mul_f32 v[6:7], v[6:7], v[88:89]
	v_pk_mul_f32 v[88:89], v[118:119], v[120:121]
	v_cvt_pk_bf16_f32 v7, v6, v7
	v_pk_mul_f32 v[88:89], v[88:89], v[90:91]
	v_mul_f32_e32 v93, 0xbfb8aa3b, v107
	v_cvt_pk_bf16_f32 v6, v88, v89
	v_mul_f32_e32 v88, 0xbfb8aa3b, v108
	v_exp_f32_e32 v90, v88
	v_mul_f32_e32 v88, 0xbfb8aa3b, v109
	v_exp_f32_e32 v91, v88
	v_exp_f32_e32 v92, v92
	v_exp_f32_e32 v93, v93
	v_add_f32_e32 v90, 1.0, v90
	v_add_f32_e32 v91, 1.0, v91
	v_rcp_f32_e32 v90, v90
	v_rcp_f32_e32 v91, v91
	v_add_f32_e32 v92, 1.0, v92
	v_add_f32_e32 v93, 1.0, v93
	v_rcp_f32_e32 v92, v92
	v_rcp_f32_e32 v93, v93
	v_pk_mul_f32 v[88:89], v[108:109], v[112:113]
	v_mov_b32_dpp v95, v86 row_ror:15 row_mask:0xf bank_mask:0xf bound_ctrl:1
	v_pk_mul_f32 v[88:89], v[88:89], v[90:91]
	v_pk_mul_f32 v[90:91], v[106:107], v[110:111]
	v_cvt_pk_bf16_f32 v89, v88, v89
	v_pk_mul_f32 v[90:91], v[90:91], v[92:93]
	v_mov_b32_dpp v93, v38 row_ror:15 row_mask:0xf bank_mask:0xf bound_ctrl:1
	v_cvt_pk_bf16_f32 v88, v90, v91
	v_mov_b32_dpp v90, v38 row_ror:1 row_mask:0xf bank_mask:0xf bound_ctrl:1
	s_waitcnt lgkmcnt(1)
	v_cndmask_b32_e64 v78, v90, v78, s[10:11]
	v_mov_b32_dpp v91, v46 row_ror:1 row_mask:0xf bank_mask:0xf bound_ctrl:1
	s_waitcnt lgkmcnt(0)
	v_fma_f32 v78, v62, v78, v66
	s_waitcnt lgkmcnt(0)
	v_cndmask_b32_e64 v90, v91, v74, s[10:11]
	v_cndmask_b32_e64 v74, v93, v95, s[12:13]
	v_fma_f32 v78, v58, v38, v78
	v_mov_b32_dpp v94, v46 row_ror:15 row_mask:0xf bank_mask:0xf bound_ctrl:1
	v_mov_b32_dpp v93, v84 row_ror:15 row_mask:0xf bank_mask:0xf bound_ctrl:1
	v_fma_f32 v74, v54, v74, v78
	v_cndmask_b32_e64 v91, v94, v93, s[12:13]
	v_mul_f32_e32 v78, 0xbfb8aa3b, v74
	v_exp_f32_e32 v94, v78
	s_waitcnt lgkmcnt(0)
	v_fma_f32 v78, v34, v90, v42
	v_mov_b32_dpp v96, v39 row_ror:15 row_mask:0xf bank_mask:0xf bound_ctrl:1
	v_fma_f32 v78, v26, v46, v78
	v_add_f32_e32 v90, 1.0, v94
	v_fma_f32 v78, v30, v91, v78
	v_mov_b32_dpp v91, v39 row_ror:1 row_mask:0xf bank_mask:0xf bound_ctrl:1
	v_mov_b32_dpp v94, v47 row_ror:1 row_mask:0xf bank_mask:0xf bound_ctrl:1
	v_cndmask_b32_e64 v79, v91, v79, s[10:11]
	v_cndmask_b32_e64 v91, v94, v75, s[10:11]
	v_mov_b32_dpp v94, v87 row_ror:15 row_mask:0xf bank_mask:0xf bound_ctrl:1
	v_fma_f32 v79, v63, v79, v67
	v_cndmask_b32_e64 v75, v96, v94, s[12:13]
	v_fma_f32 v79, v59, v39, v79
	v_rcp_f32_e32 v90, v90
	v_fma_f32 v75, v55, v75, v79
	v_fma_f32 v98, v35, v91, v43
	v_mov_b32_dpp v97, v47 row_ror:15 row_mask:0xf bank_mask:0xf bound_ctrl:1
	v_mul_f32_e32 v79, 0xbfb8aa3b, v75
	v_exp_f32_e32 v79, v79
	v_mov_b32_dpp v96, v85 row_ror:15 row_mask:0xf bank_mask:0xf bound_ctrl:1
	v_cndmask_b32_e64 v97, v97, v96, s[12:13]
	v_mov_b32_dpp v100, v83 row_ror:15 row_mask:0xf bank_mask:0xf bound_ctrl:1
	v_add_f32_e32 v79, 1.0, v79
	v_rcp_f32_e32 v91, v79
	v_fma_f32 v79, v27, v47, v98
	v_mov_b32_dpp v98, v8 row_ror:15 row_mask:0xf bank_mask:0xf bound_ctrl:1
	v_fma_f32 v79, v31, v97, v79
	v_mov_b32_dpp v97, v82 row_ror:15 row_mask:0xf bank_mask:0xf bound_ctrl:1
	v_pk_mul_f32 v[74:75], v[74:75], v[78:79]
	v_mov_b32_dpp v78, v40 row_ror:1 row_mask:0xf bank_mask:0xf bound_ctrl:1
	v_cndmask_b32_e64 v78, v78, v80, s[10:11]
	v_pk_mul_f32 v[74:75], v[74:75], v[90:91]
	v_mov_b32_dpp v79, v48 row_ror:1 row_mask:0xf bank_mask:0xf bound_ctrl:1
; #define PG8_GAS __attribute__((address_space(1)))
; __device__ __forceinline__ unsigned cvt_pk_bf16(float lo, float hi) { const f32x2c v = {lo, hi}; return __builtin_bit_cast(unsigned, __builtin_convertvector(v, bf16x2c)); }
; __device__ __forceinline__ float fma_s(float a, float b, float c) { float d; asm("v_fma_f32 %0, %1, %2, %3" : "=v"(d) : "v"(a), "v"(b), "v"(c)); return d; }
; #define PG8_ROR1(x) dpp_ror1(x)
; #define PG8_ROR15(x) dpp_ror15(x)
;     __device__ __forceinline__ void run(f32x4 (&acc)[2][2][4][2], const Unit& un, int wr, int wc, int fr, int fq, PG8_LAS unsigned char* xl) const {
;     ...
;                 for (int m = 0; m < 4; ++m) {
;                     float o[4];
; #pragma unroll
;                     for (int e = 0; e < 4; ++e) {
;                         const float g = acc[ai][0][m][n][e], v = acc[ai][1][m][n][e];
;                         const float gpe = m > 0 ? PG8_ROR1(acc[ai][0][m - 1][n][e]) : hpg[e], vpe = m > 0 ? PG8_ROR1(acc[ai][1][m - 1][n][e]) : hpv[e];
;                         const float gne = m < 3 ? PG8_ROR15(acc[ai][0][m + 1][n][e]) : hng[e], vne = m < 3 ? PG8_ROR15(acc[ai][1][m + 1][n][e]) : hnv[e];
;                         const float gpi = PG8_ROR1(g), vpi = PG8_ROR1(v), gni = PG8_ROR15(g), vni = PG8_ROR15(v);
;                         const float gp = e0 ? gpe : gpi, vp = e0 ? vpe : vpi, gn = e15 ? gne : gni, vn = e15 ? vne : vni;
;                         const float cg = fma_s(w2g[e], gn, fma_s(w1g[e], g, fma_s(w0g[e], gp, bg[e]))), cv = fma_s(w2v[e], vn, fma_s(w1v[e], v, fma_s(w0v[e], vp, bv[e])));
;                         o[e] = (cg * cv) * __builtin_amdgcn_rcpf(1.0f + __builtin_amdgcn_exp2f(cg * -1.4426950408889634f));
;                     }
;                     if (n == 0) { keep[m].x = cvt_pk_bf16(o[0], o[1]); keep[m].y = cvt_pk_bf16(o[2], o[3]); }
;                     else { u32x4 w; w.x = keep[m].x; w.y = keep[m].y; w.z = cvt_pk_bf16(o[0], o[1]); w.w = cvt_pk_bf16(o[2], o[3]);
;                         *(PG8_GAS u32x4*)(act + (size_t)(row0 + ai * HALF + m * 16) * dff + j - 4) = w; }
	v_mov_b32_dpp v90, v40 row_ror:15 row_mask:0xf bank_mask:0xf bound_ctrl:1
	v_fma_f32 v78, v64, v78, v68
	v_cndmask_b32_e64 v79, v79, v76, s[10:11]
	v_cndmask_b32_e64 v76, v90, v97, s[12:13]
	v_fma_f32 v78, v60, v40, v78
	v_mov_b32_dpp v91, v48 row_ror:15 row_mask:0xf bank_mask:0xf bound_ctrl:1
	v_fma_f32 v76, v56, v76, v78
	v_cndmask_b32_e64 v80, v91, v98, s[12:13]
	v_mul_f32_e32 v78, 0xbfb8aa3b, v76
	v_exp_f32_e32 v90, v78
	v_fma_f32 v78, v36, v79, v44
	v_mov_b32_dpp v91, v41 row_ror:15 row_mask:0xf bank_mask:0xf bound_ctrl:1
	v_fma_f32 v78, v28, v48, v78
	v_add_f32_e32 v79, 1.0, v90
	v_fma_f32 v78, v32, v80, v78
	v_rcp_f32_e32 v80, v79
	v_mov_b32_dpp v90, v49 row_ror:1 row_mask:0xf bank_mask:0xf bound_ctrl:1
	v_mov_b32_dpp v79, v41 row_ror:1 row_mask:0xf bank_mask:0xf bound_ctrl:1
	v_cndmask_b32_e64 v79, v79, v81, s[10:11]
	v_fma_f32 v79, v65, v79, v69
	v_cndmask_b32_e64 v81, v90, v77, s[10:11]
	v_cndmask_b32_e64 v77, v91, v100, s[12:13]
	v_fma_f32 v79, v61, v41, v79
	v_mov_b32_dpp v99, v49 row_ror:15 row_mask:0xf bank_mask:0xf bound_ctrl:1
	v_fma_f32 v77, v57, v77, v79
	v_mov_b32_dpp v101, v9 row_ror:15 row_mask:0xf bank_mask:0xf bound_ctrl:1
	v_mul_f32_e32 v79, 0xbfb8aa3b, v77
	v_exp_f32_e32 v79, v79
	v_fma_f32 v91, v37, v81, v45
	v_cndmask_b32_e64 v90, v99, v101, s[12:13]
	v_mov_b32_dpp v46, v46 row_ror:1 row_mask:0xf bank_mask:0xf bound_ctrl:1
	v_add_f32_e32 v79, 1.0, v79
	v_rcp_f32_e32 v81, v79
	v_fma_f32 v79, v29, v49, v91
	v_add_u32_e32 v92, 0x80, v172
	v_fma_f32 v79, v33, v90, v79
	v_cvt_pk_bf16_f32 v90, v74, v75
	v_pk_mul_f32 v[76:77], v[76:77], v[78:79]
	v_mov_b32_dpp v79, v84 row_ror:1 row_mask:0xf bank_mask:0xf bound_ctrl:1
	v_cndmask_b32_e64 v46, v79, v46, s[10:11]
	v_pk_mul_f32 v[76:77], v[76:77], v[80:81]
	v_mov_b64_e32 v[74:75], s[24:25]
	v_fma_f32 v46, v34, v46, v42
	v_cvt_pk_bf16_f32 v91, v76, v77
	v_mad_i64_i32 v[76:77], s[14:15], v92, s5, v[74:75]
	v_mov_b32_dpp v38, v38 row_ror:1 row_mask:0xf bank_mask:0xf bound_ctrl:1
	v_mov_b32_dpp v78, v86 row_ror:1 row_mask:0xf bank_mask:0xf bound_ctrl:1
	v_fma_f32 v46, v26, v84, v46
	v_mov_b32_dpp v39, v39 row_ror:1 row_mask:0xf bank_mask:0xf bound_ctrl:1
	v_mov_b32_dpp v84, v87 row_ror:1 row_mask:0xf bank_mask:0xf bound_ctrl:1
	v_lshl_add_u64 v[76:77], v[76:77], 0, v[146:147]
	v_cndmask_b32_e64 v38, v78, v38, s[10:11]
	v_mov_b32_dpp v81, v14 row_ror:15 row_mask:0xf bank_mask:0xf bound_ctrl:1
	v_cndmask_b32_e64 v39, v84, v39, s[10:11]
	global_store_dwordx4 v[76:77], v[88:91], off
	v_mov_b32_dpp v80, v16 row_ror:15 row_mask:0xf bank_mask:0xf bound_ctrl:1
	v_cndmask_b32_e64 v77, v93, v81, s[12:13]
	v_fma_f32 v38, v62, v38, v66
	v_mov_b32_dpp v88, v17 row_ror:15 row_mask:0xf bank_mask:0xf bound_ctrl:1
	v_fma_f32 v39, v63, v39, v67
	v_cndmask_b32_e64 v76, v95, v80, s[12:13]
	v_fma_f32 v38, v58, v86, v38
	v_fma_f32 v46, v30, v77, v46
	v_cndmask_b32_e64 v77, v94, v88, s[12:13]
	v_fma_f32 v39, v59, v87, v39
	v_fma_f32 v38, v54, v76, v38
	v_mov_b32_dpp v47, v47 row_ror:1 row_mask:0xf bank_mask:0xf bound_ctrl:1
	v_mul_f32_e32 v76, 0xbfb8aa3b, v38
	v_fma_f32 v39, v55, v77, v39
	v_exp_f32_e32 v76, v76
	v_mul_f32_e32 v77, 0xbfb8aa3b, v39
	v_exp_f32_e32 v77, v77
	v_mov_b32_dpp v86, v85 row_ror:1 row_mask:0xf bank_mask:0xf bound_ctrl:1
	v_add_f32_e32 v76, 1.0, v76
	v_cndmask_b32_e64 v47, v86, v47, s[10:11]
	v_add_f32_e32 v77, 1.0, v77
	v_rcp_f32_e32 v76, v76
	v_fma_f32 v47, v35, v47, v43
	v_rcp_f32_e32 v77, v77
	v_mov_b32_dpp v87, v15 row_ror:15 row_mask:0xf bank_mask:0xf bound_ctrl:1
	v_fma_f32 v47, v27, v85, v47
	v_cndmask_b32_e64 v89, v96, v87, s[12:13]
	v_fma_f32 v47, v31, v89, v47
	v_mov_b32_dpp v40, v40 row_ror:1 row_mask:0xf bank_mask:0xf bound_ctrl:1
	v_pk_mul_f32 v[38:39], v[38:39], v[46:47]
	v_mov_b32_dpp v46, v48 row_ror:1 row_mask:0xf bank_mask:0xf bound_ctrl:1
	v_mov_b32_dpp v48, v82 row_ror:1 row_mask:0xf bank_mask:0xf bound_ctrl:1
	v_cndmask_b32_e64 v40, v48, v40, s[10:11]
	v_pk_mul_f32 v[38:39], v[38:39], v[76:77]
	v_mov_b32_dpp v77, v12 row_ror:15 row_mask:0xf bank_mask:0xf bound_ctrl:1
	v_fma_f32 v40, v64, v40, v68
	v_cndmask_b32_e64 v47, v97, v77, s[12:13]
	v_fma_f32 v40, v60, v82, v40
	v_mov_b32_dpp v76, v8 row_ror:1 row_mask:0xf bank_mask:0xf bound_ctrl:1
	v_fma_f32 v40, v56, v47, v40
	v_cndmask_b32_e64 v46, v76, v46, s[10:11]
	v_mul_f32_e32 v47, 0xbfb8aa3b, v40
	v_exp_f32_e32 v47, v47
	v_fma_f32 v46, v36, v46, v44
	v_mov_b32_dpp v41, v41 row_ror:1 row_mask:0xf bank_mask:0xf bound_ctrl:1
	v_fma_f32 v8, v28, v8, v46
	v_add_f32_e32 v46, 1.0, v47
	v_mov_b32_dpp v47, v49 row_ror:1 row_mask:0xf bank_mask:0xf bound_ctrl:1
	v_mov_b32_dpp v49, v83 row_ror:1 row_mask:0xf bank_mask:0xf bound_ctrl:1
	v_mov_b32_dpp v85, v10 row_ror:15 row_mask:0xf bank_mask:0xf bound_ctrl:1
	v_cndmask_b32_e64 v41, v49, v41, s[10:11]
	v_cndmask_b32_e64 v89, v98, v85, s[12:13]
	v_fma_f32 v41, v65, v41, v69
	v_fma_f32 v8, v32, v89, v8
	v_mov_b32_dpp v82, v9 row_ror:1 row_mask:0xf bank_mask:0xf bound_ctrl:1
	v_fma_f32 v41, v61, v83, v41
	v_cndmask_b32_e64 v47, v82, v47, s[10:11]
	v_mov_b32_dpp v89, v13 row_ror:15 row_mask:0xf bank_mask:0xf bound_ctrl:1
	v_cndmask_b32_e64 v90, v100, v89, s[12:13]
	v_fma_f32 v41, v57, v90, v41
	v_fma_f32 v92, v37, v47, v45
	v_rcp_f32_e32 v46, v46
	v_mul_f32_e32 v83, 0xbfb8aa3b, v41
	v_exp_f32_e32 v83, v83
	v_mov_b32_dpp v90, v11 row_ror:15 row_mask:0xf bank_mask:0xf bound_ctrl:1
	v_fma_f32 v9, v29, v9, v92
	v_cndmask_b32_e64 v91, v101, v90, s[12:13]
	v_add_f32_e32 v47, 1.0, v83
	v_rcp_f32_e32 v47, v47
	v_fma_f32 v9, v33, v91, v9
	s_nop 0
	v_pk_mul_f32 v[8:9], v[40:41], v[8:9]
	s_nop 0
	v_pk_mul_f32 v[40:41], v[8:9], v[46:47]
	v_cvt_pk_bf16_f32 v8, v38, v39
; #define PG8_GAS __attribute__((address_space(1)))
; __device__ __forceinline__ unsigned cvt_pk_bf16(float lo, float hi) { const f32x2c v = {lo, hi}; return __builtin_bit_cast(unsigned, __builtin_convertvector(v, bf16x2c)); }
; __device__ __forceinline__ float fma_s(float a, float b, float c) { float d; asm("v_fma_f32 %0, %1, %2, %3" : "=v"(d) : "v"(a), "v"(b), "v"(c)); return d; }
; #define PG8_ROR1(x) dpp_ror1(x)
; #define PG8_ROR15(x) dpp_ror15(x)
;     __device__ __forceinline__ void run(f32x4 (&acc)[2][2][4][2], const Unit& un, int wr, int wc, int fr, int fq, PG8_LAS unsigned char* xl) const {
;     ...
;                 for (int m = 0; m < 4; ++m) {
;                     float o[4];
; #pragma unroll
;                     for (int e = 0; e < 4; ++e) {
;                         const float g = acc[ai][0][m][n][e], v = acc[ai][1][m][n][e];
;                         const float gpe = m > 0 ? PG8_ROR1(acc[ai][0][m - 1][n][e]) : hpg[e], vpe = m > 0 ? PG8_ROR1(acc[ai][1][m - 1][n][e]) : hpv[e];
;                         const float gne = m < 3 ? PG8_ROR15(acc[ai][0][m + 1][n][e]) : hng[e], vne = m < 3 ? PG8_ROR15(acc[ai][1][m + 1][n][e]) : hnv[e];
;                         const float gpi = PG8_ROR1(g), vpi = PG8_ROR1(v), gni = PG8_ROR15(g), vni = PG8_ROR15(v);
;                         const float gp = e0 ? gpe : gpi, vp = e0 ? vpe : vpi, gn = e15 ? gne : gni, vn = e15 ? vne : vni;
;                         const float cg = fma_s(w2g[e], gn, fma_s(w1g[e], g, fma_s(w0g[e], gp, bg[e]))), cv = fma_s(w2v[e], vn, fma_s(w1v[e], v, fma_s(w0v[e], vp, bv[e])));
;                         o[e] = (cg * cv) * __builtin_amdgcn_rcpf(1.0f + __builtin_amdgcn_exp2f(cg * -1.4426950408889634f));
;                     }
;                     if (n == 0) { keep[m].x = cvt_pk_bf16(o[0], o[1]); keep[m].y = cvt_pk_bf16(o[2], o[3]); }
;                     else { u32x4 w; w.x = keep[m].x; w.y = keep[m].y; w.z = cvt_pk_bf16(o[0], o[1]); w.w = cvt_pk_bf16(o[2], o[3]);
;                         *(PG8_GAS u32x4*)(act + (size_t)(row0 + ai * HALF + m * 16) * dff + j - 4) = w; }
	v_add_u32_e32 v38, 0x90, v172
	v_mad_i64_i32 v[38:39], s[14:15], v38, s5, v[74:75]
	v_cvt_pk_bf16_f32 v9, v40, v41
	v_lshl_add_u64 v[38:39], v[38:39], 0, v[146:147]
	global_store_dwordx4 v[38:39], v[6:9], off
	v_mov_b32_dpp v40, v15 row_ror:1 row_mask:0xf bank_mask:0xf bound_ctrl:1
	v_mov_b32_dpp v38, v16 row_ror:1 row_mask:0xf bank_mask:0xf bound_ctrl:1
	v_cndmask_b32_e64 v8, v38, v78, s[10:11]
	v_mov_b32_dpp v6, v22 row_ror:15 row_mask:0xf bank_mask:0xf bound_ctrl:1
	v_fma_f32 v8, v62, v8, v66
	v_cndmask_b32_e64 v6, v80, v6, s[12:13]
	v_fma_f32 v8, v58, v16, v8
	v_mov_b32_dpp v39, v14 row_ror:1 row_mask:0xf bank_mask:0xf bound_ctrl:1
	v_fma_f32 v6, v54, v6, v8
	v_mov_b32_dpp v7, v18 row_ror:15 row_mask:0xf bank_mask:0xf bound_ctrl:1
	v_mul_f32_e32 v8, 0xbfb8aa3b, v6
	v_exp_f32_e32 v16, v8
	v_cndmask_b32_e64 v9, v39, v79, s[10:11]
	v_fma_f32 v8, v34, v9, v42
	v_cndmask_b32_e64 v7, v81, v7, s[12:13]
	v_fma_f32 v8, v26, v14, v8
	v_mov_b32_dpp v14, v17 row_ror:1 row_mask:0xf bank_mask:0xf bound_ctrl:1
	v_fma_f32 v8, v30, v7, v8
	v_add_f32_e32 v7, 1.0, v16
	v_rcp_f32_e32 v16, v7
	v_cndmask_b32_e64 v41, v14, v84, s[10:11]
	v_mov_b32_dpp v7, v23 row_ror:15 row_mask:0xf bank_mask:0xf bound_ctrl:1
	v_cndmask_b32_e64 v7, v88, v7, s[12:13]
	v_fma_f32 v41, v63, v41, v67
	v_mov_b32_dpp v9, v19 row_ror:15 row_mask:0xf bank_mask:0xf bound_ctrl:1
	v_fma_f32 v17, v59, v17, v41
	v_cndmask_b32_e64 v41, v40, v86, s[10:11]
	v_fma_f32 v7, v55, v7, v17
	v_cndmask_b32_e64 v9, v87, v9, s[12:13]
	v_mul_f32_e32 v17, 0xbfb8aa3b, v7
	v_exp_f32_e32 v17, v17
	v_fma_f32 v41, v35, v41, v43
	v_mov_b32_dpp v46, v11 row_ror:1 row_mask:0xf bank_mask:0xf bound_ctrl:1
	v_fma_f32 v15, v27, v15, v41
	v_add_f32_e32 v17, 1.0, v17
	v_rcp_f32_e32 v17, v17
	v_fma_f32 v9, v31, v9, v15
	v_mov_b32_dpp v15, v12 row_ror:1 row_mask:0xf bank_mask:0xf bound_ctrl:1
	v_pk_mul_f32 v[6:7], v[6:7], v[8:9]
	v_mov_b32_dpp v8, v24 row_ror:15 row_mask:0xf bank_mask:0xf bound_ctrl:1
	v_pk_mul_f32 v[6:7], v[6:7], v[16:17]
	v_cndmask_b32_e64 v17, v15, v48, s[10:11]
	v_cndmask_b32_e64 v8, v77, v8, s[12:13]
	v_fma_f32 v17, v64, v17, v68
	v_mov_b32_dpp v9, v20 row_ror:15 row_mask:0xf bank_mask:0xf bound_ctrl:1
	v_fma_f32 v12, v60, v12, v17
	v_mov_b32_dpp v16, v10 row_ror:1 row_mask:0xf bank_mask:0xf bound_ctrl:1
	v_fma_f32 v8, v56, v8, v12
	v_cndmask_b32_e64 v41, v16, v76, s[10:11]
	v_mul_f32_e32 v12, 0xbfb8aa3b, v8
	v_exp_f32_e32 v12, v12
	v_cndmask_b32_e64 v9, v85, v9, s[12:13]
	v_fma_f32 v17, v36, v41, v44
	v_mov_b32_dpp v41, v13 row_ror:1 row_mask:0xf bank_mask:0xf bound_ctrl:1
	v_fma_f32 v10, v28, v10, v17
	v_cndmask_b32_e64 v47, v41, v49, s[10:11]
	v_fma_f32 v10, v32, v9, v10
	v_add_f32_e32 v9, 1.0, v12
	v_rcp_f32_e32 v12, v9
	v_fma_f32 v47, v65, v47, v69
	v_mov_b32_dpp v17, v21 row_ror:15 row_mask:0xf bank_mask:0xf bound_ctrl:1
	v_mov_b32_dpp v9, v25 row_ror:15 row_mask:0xf bank_mask:0xf bound_ctrl:1
	v_cndmask_b32_e64 v9, v89, v9, s[12:13]
	v_fma_f32 v13, v61, v13, v47
	v_cndmask_b32_e64 v47, v46, v82, s[10:11]
	v_fma_f32 v9, v57, v9, v13
	v_fma_f32 v47, v37, v47, v45
	v_cndmask_b32_e64 v17, v90, v17, s[12:13]
	v_mul_f32_e32 v13, 0xbfb8aa3b, v9
	v_exp_f32_e32 v13, v13
	v_fma_f32 v11, v29, v11, v47
	v_cvt_pk_bf16_f32 v6, v6, v7
	v_fma_f32 v11, v33, v17, v11
	v_add_f32_e32 v13, 1.0, v13
	v_rcp_f32_e32 v13, v13
	v_pk_mul_f32 v[8:9], v[8:9], v[10:11]
	v_mov_b32_dpp v10, v19 row_ror:15 row_mask:0xf bank_mask:0xf bound_ctrl:1
	v_cndmask_b32_e64 v10, v10, v51, s[12:13]
	v_pk_mul_f32 v[8:9], v[8:9], v[12:13]
	v_mov_b32_dpp v11, v25 row_ror:15 row_mask:0xf bank_mask:0xf bound_ctrl:1
	v_cvt_pk_bf16_f32 v7, v8, v9
	v_add_u32_e32 v8, 0xa0, v172
	v_mad_i64_i32 v[8:9], s[14:15], v8, s5, v[74:75]
	v_lshl_add_u64 v[8:9], v[8:9], 0, v[146:147]
	global_store_dwordx4 v[8:9], v[4:7], off
	v_cndmask_b32_e64 v11, v11, v73, s[12:13]
	v_mov_b32_dpp v9, v23 row_ror:15 row_mask:0xf bank_mask:0xf bound_ctrl:1
	v_mov_b32_dpp v4, v22 row_ror:1 row_mask:0xf bank_mask:0xf bound_ctrl:1
	v_cndmask_b32_e64 v4, v4, v38, s[10:11]
	v_mov_b32_dpp v6, v22 row_ror:15 row_mask:0xf bank_mask:0xf bound_ctrl:1
	v_fma_f32 v4, v62, v4, v66
	v_cndmask_b32_e64 v6, v6, v70, s[12:13]
	v_fma_f32 v4, v58, v22, v4
	v_mov_b32_dpp v5, v18 row_ror:1 row_mask:0xf bank_mask:0xf bound_ctrl:1
	v_fma_f32 v4, v54, v6, v4
	v_cndmask_b32_e64 v5, v5, v39, s[10:11]
	v_mul_f32_e32 v6, 0xbfb8aa3b, v4
	v_exp_f32_e32 v8, v6
	v_fma_f32 v5, v34, v5, v42
	v_mov_b32_dpp v7, v18 row_ror:15 row_mask:0xf bank_mask:0xf bound_ctrl:1
	v_fma_f32 v5, v26, v18, v5
	v_cndmask_b32_e64 v7, v7, v50, s[12:13]
	v_fma_f32 v6, v30, v7, v5
	v_add_f32_e32 v5, 1.0, v8
	v_rcp_f32_e32 v8, v5
	v_cndmask_b32_e64 v9, v9, v71, s[12:13]
	v_mov_b32_dpp v5, v23 row_ror:1 row_mask:0xf bank_mask:0xf bound_ctrl:1
	v_cndmask_b32_e64 v5, v5, v14, s[10:11]
	v_fma_f32 v5, v63, v5, v67
	v_mov_b32_dpp v7, v19 row_ror:1 row_mask:0xf bank_mask:0xf bound_ctrl:1
	v_fma_f32 v5, v59, v23, v5
	v_cndmask_b32_e64 v7, v7, v40, s[10:11]
	v_fma_f32 v5, v55, v9, v5
	v_fma_f32 v7, v35, v7, v43
	v_mov_b32_dpp v12, v21 row_ror:15 row_mask:0xf bank_mask:0xf bound_ctrl:1
	v_mul_f32_e32 v9, 0xbfb8aa3b, v5
	v_exp_f32_e32 v9, v9
	v_fma_f32 v7, v27, v19, v7
	v_cndmask_b32_e64 v12, v12, v53, s[12:13]
	v_fma_f32 v7, v31, v10, v7
	v_add_f32_e32 v9, 1.0, v9
	v_rcp_f32_e32 v9, v9
	v_pk_mul_f32 v[4:5], v[4:5], v[6:7]
	v_mov_b32_dpp v6, v24 row_ror:1 row_mask:0xf bank_mask:0xf bound_ctrl:1
	v_cndmask_b32_e64 v6, v6, v15, s[10:11]
	v_pk_mul_f32 v[4:5], v[4:5], v[8:9]
	v_mov_b32_dpp v8, v24 row_ror:15 row_mask:0xf bank_mask:0xf bound_ctrl:1
	v_fma_f32 v6, v64, v6, v68
	v_cndmask_b32_e64 v8, v8, v72, s[12:13]
	v_fma_f32 v6, v60, v24, v6
	v_mov_b32_dpp v7, v20 row_ror:1 row_mask:0xf bank_mask:0xf bound_ctrl:1
	v_fma_f32 v6, v56, v8, v6
	v_cndmask_b32_e64 v7, v7, v16, s[10:11]
	v_mul_f32_e32 v8, 0xbfb8aa3b, v6
	v_exp_f32_e32 v10, v8
	v_fma_f32 v7, v36, v7, v44
	v_mov_b32_dpp v9, v20 row_ror:15 row_mask:0xf bank_mask:0xf bound_ctrl:1
	v_fma_f32 v7, v28, v20, v7
	v_cndmask_b32_e64 v9, v9, v52, s[12:13]
	v_fma_f32 v8, v32, v9, v7
	v_add_f32_e32 v7, 1.0, v10
	v_rcp_f32_e32 v10, v7
	v_mov_b32_dpp v9, v21 row_ror:1 row_mask:0xf bank_mask:0xf bound_ctrl:1
	v_mov_b32_dpp v7, v25 row_ror:1 row_mask:0xf bank_mask:0xf bound_ctrl:1
	v_cndmask_b32_e64 v7, v7, v41, s[10:11]
	v_fma_f32 v7, v65, v7, v69
	v_cndmask_b32_e64 v9, v9, v46, s[10:11]
	v_fma_f32 v7, v61, v25, v7
	v_fma_f32 v9, v37, v9, v45
	v_cvt_pk_bf16_f32 v4, v4, v5
	v_fma_f32 v7, v57, v11, v7
	v_fma_f32 v9, v29, v21, v9
	s_nop 0
	v_mul_f32_e32 v11, 0xbfb8aa3b, v7
	v_exp_f32_e32 v11, v11
	v_fma_f32 v9, v33, v12, v9
	s_nop 0
	v_pk_mul_f32 v[6:7], v[6:7], v[8:9]
	v_add_f32_e32 v11, 1.0, v11
	v_rcp_f32_e32 v11, v11
	s_nop 0
	v_pk_mul_f32 v[6:7], v[6:7], v[10:11]
	s_nop 0
	v_cvt_pk_bf16_f32 v5, v6, v7
	v_add_u32_e32 v6, 0xb0, v172
	v_mad_i64_i32 v[6:7], s[10:11], v6, s5, v[74:75]
	v_lshl_add_u64 v[6:7], v[6:7], 0, v[146:147]
	global_store_dwordx4 v[6:7], v[2:5], off
	s_andn2_b64 vcc, exec, s[8:9]
	s_mov_b64 s[8:9], -1
	s_cbranch_vccnz .LBB0_766
; #define PG8_BAR __builtin_amdgcn_s_barrier()
; template <class Epi, class Sched, bool ALIGN_EPI = false, bool SP2 = false, bool F8 = false>
; __device__ __forceinline__ void gemm_phase(PG8_LAS unsigned char* lds, const Gemm g, const Sched& S, const Epi& E) {
;     ...
;         if (!has_next) break;
; #pragma unroll
;         for (int a = 0; a < 2; ++a)
; #pragma unroll
;             for (int b = 0; b < 2; ++b)
; #pragma unroll
;                 for (int m = 0; m < 4; ++m)
; #pragma unroll
;                     for (int n = 0; n < 2; ++n) acc[a][b][m][n] = (f32x4){0.f, 0.f, 0.f, 0.f};
;         cur = nxt; cA = nA; cB = nB; ++ui;
;         if constexpr (ALIGN_EPI) { if (wr == 1) PG8_BAR; }
;     }
	s_andn2_b64 vcc, exec, s[30:31]
	s_cbranch_vccnz .LBB0_765
	s_barrier
	s_branch .LBB0_765

; __global__ void __launch_bounds__(NWAVES * 64, 2) fwd_kernel(Args args) {
	.amdhsa_kernel _Z10fwd_kernel4Args
		.amdhsa_group_segment_fixed_size 0
		.amdhsa_private_segment_fixed_size 0
		.amdhsa_kernarg_size 400
		.amdhsa_user_sgpr_count 2
		.amdhsa_user_sgpr_dispatch_ptr 0
		.amdhsa_user_sgpr_queue_ptr 0
		.amdhsa_user_sgpr_kernarg_segment_ptr 1
		.amdhsa_user_sgpr_dispatch_id 0
		.amdhsa_user_sgpr_kernarg_preload_length 0
		.amdhsa_user_sgpr_kernarg_preload_offset 0
		.amdhsa_user_sgpr_private_segment_size 0
		.amdhsa_uses_dynamic_stack 0
		.amdhsa_enable_private_segment 0
		.amdhsa_system_sgpr_workgroup_id_x 1
		.amdhsa_system_sgpr_workgroup_id_y 0
		.amdhsa_system_sgpr_workgroup_id_z 0
		.amdhsa_system_sgpr_workgroup_info 0
		.amdhsa_system_vgpr_workitem_id 0
		.amdhsa_next_free_vgpr 255
		.amdhsa_next_free_sgpr 102
		.amdhsa_accum_offset 256
		.amdhsa_reserve_vcc 1
		.amdhsa_float_round_mode_32 0
		.amdhsa_float_round_mode_16_64 0
		.amdhsa_float_denorm_mode_32 3
		.amdhsa_float_denorm_mode_16_64 3
		.amdhsa_dx10_clamp 1
		.amdhsa_ieee_mode 1
		.amdhsa_fp16_overflow 0
		.amdhsa_tg_split 0
		.amdhsa_exception_fp_ieee_invalid_op 0
		.amdhsa_exception_fp_denorm_src 0
		.amdhsa_exception_fp_ieee_div_zero 0
		.amdhsa_exception_fp_ieee_overflow 0
		.amdhsa_exception_fp_ieee_underflow 0
		.amdhsa_exception_fp_ieee_inexact 0
		.amdhsa_exception_int_div_zero 0
	.end_amdhsa_kernel

; __global__ void __launch_bounds__(NWAVES * 64, 2) fwd_kernel(Args args) {
.Lfunc_end0:
	.size	_Z10fwd_kernel4Args, .Lfunc_end0-_Z10fwd_kernel4Args
	.set _Z10fwd_kernel4Args.num_vgpr, 255
	.set _Z10fwd_kernel4Args.num_agpr, 0
	.set _Z10fwd_kernel4Args.numbered_sgpr, 102
	.set _Z10fwd_kernel4Args.num_named_barrier, 0
	.set _Z10fwd_kernel4Args.private_seg_size, 0
	.set _Z10fwd_kernel4Args.uses_vcc, 1
	.set _Z10fwd_kernel4Args.uses_flat_scratch, 0
	.set _Z10fwd_kernel4Args.has_dyn_sized_stack, 0
	.set _Z10fwd_kernel4Args.has_recursion, 0
	.set _Z10fwd_kernel4Args.has_indirect_call, 0

; template <int OFF> __device__ __forceinline__ unsigned long long karg_u64() {
;     auto kp = __builtin_amdgcn_kernarg_segment_ptr(); unsigned long long v;
;     asm volatile("s_load_dwordx2 %0, %1, %2\n\ts_waitcnt lgkmcnt(0)" : "=s"(v) : "s"(kp), "i"(OFF) : "memory"); return v;
; }
; __global__ void __launch_bounds__(NWAVES * 64, 2) fwd_kernel(Args args) {
amdhsa.kernels:
  - .agpr_count:     0
    .args:
      - .offset:         0
        .size:           144
        .value_kind:     by_value
      - .offset:         144
        .size:           4
        .value_kind:     hidden_block_count_x
      - .offset:         148
        .size:           4
        .value_kind:     hidden_block_count_y
      - .offset:         152
        .size:           4
        .value_kind:     hidden_block_count_z
      - .offset:         156
        .size:           2
        .value_kind:     hidden_group_size_x
      - .offset:         158
        .size:           2
        .value_kind:     hidden_group_size_y
      - .offset:         160
        .size:           2
        .value_kind:     hidden_group_size_z
      - .offset:         162
        .size:           2
        .value_kind:     hidden_remainder_x
      - .offset:         164
        .size:           2
        .value_kind:     hidden_remainder_y
      - .offset:         166
        .size:           2
        .value_kind:     hidden_remainder_z
      - .offset:         184
        .size:           8
        .value_kind:     hidden_global_offset_x
      - .offset:         192
        .size:           8
        .value_kind:     hidden_global_offset_y
      - .offset:         200
        .size:           8
        .value_kind:     hidden_global_offset_z
      - .offset:         208
        .size:           2
        .value_kind:     hidden_grid_dims
      - .offset:         264
        .size:           4
        .value_kind:     hidden_dynamic_lds_size
    .group_segment_fixed_size: 0
    .kernarg_segment_align: 8
    .kernarg_segment_size: 400
    .language:       OpenCL C
    .language_version:
      - 2
      - 0
    .max_flat_workgroup_size: 512
    .name:           _Z10fwd_kernel4Args
    .private_segment_fixed_size: 0
    .sgpr_count:     108
    .sgpr_spill_count: 53
    .symbol:         _Z10fwd_kernel4Args.kd
    .uniform_work_group_size: 1
    .uses_dynamic_stack: false
    .vgpr_count:     255
    .vgpr_spill_count: 0
    .wavefront_size: 64
